# early work-queue fetch at unit start for mlstm/w2/mblk/pcmp/smlstm loops
# baseline (speedup 1.0000x reference)
; #define LAS __attribute__((address_space(3)))
; #define NEXT_UNIT4() do { __syncthreads(); if (tid == 0) *UQ = (int)__hip_atomic_fetch_add(qctr, 1u, __ATOMIC_RELAXED, __HIP_MEMORY_SCOPE_AGENT); __syncthreads(); u = __builtin_amdgcn_readfirstlane(*UQ); } while (0)
; DI void p4_run(const Args& a, LAS unsigned char* lds, unsigned* qctr, const XcdBarrier& fb, unsigned* F, unsigned* F2, unsigned* F4a, unsigned* F4b) {
;     ...
;     if (tid == 0) *(volatile LAS int*)(lds + RING_BYTES + 192) = 0;
;     if (F2 != nullptr) xcd_flag_wait(fb, F2);
;     NEXT_UNIT4();
;     constexpr int CS = 32, C0 = CS + 128 * P4F_A, C1 = C0 + 256 * P4F_B, C2 = C1, C3 = C2 + 256 * P4F_C;
; #pragma unroll 1
;     while (u < CS) { if (wave == 0) scan_unit(a, u, lane); NEXT_UNIT4(); }
; #pragma unroll 1
;     while (u < C0) { const int v = (u - CS) % 128; pcmp_unit(a, lds, v >> 6, (v >> 2) & 15, v & 3, wave, lane); NEXT_UNIT4(); }
.LBB0_1301:
	v_readfirstlane_b32 s100, v0
	s_cmp_lg_u32 s100, 0
	s_cbranch_scc1 .Lnuq_pcmp
	s_mov_b64 exec, 1
	v_mov_b32_e32 v255, 1
	s_nop 3
	global_atomic_add v255, v0, v255, s[26:27] offset:768 sc0
	s_mov_b64 exec, -1

; #define LAS __attribute__((address_space(3)))
; DI unsigned pk2(float lo, float hi) { f32x2 v = {lo, hi}; bf16x2_t b = __builtin_convertvector(v, bf16x2_t); return __builtin_bit_cast(unsigned, b); }
; DI void pcmp_unit(const Args& a, LAS unsigned char* lds, int kind, int seq, int quarter, int wave, int lane) {
;     ...
;     LAS bf16_t* G = (LAS bf16_t*)lds;
;     const float* cb = (const float*)(ws + WS_CBIAS) + kind * 256;
;     __syncthreads();
; #pragma unroll
;     for (int mt = 0; mt < 2; ++mt)
; #pragma unroll
;         for (int nt = 0; nt < 2; ++nt) { const int col = 32 * wave + 16 * nt + fr; const float bv = cb[col];
; #pragma unroll
;             for (int j = 0; j < 4; ++j) G[(16 * mt + 4 * fq + j) * 264 + col] = (bf16_t)(pk2(gelu_tanh(acc[mt][nt][j] + bv), 0.f) & 0xffffu); }
;     __syncthreads();
.LBB0_1305:
	s_lshl_b32 s4, s2, 8
	s_ashr_i32 s5, s4, 31
	v_lshl_add_u64 v[10:11], s[4:5], 2, v[38:39]
	s_barrier
	global_load_dword v12, v[10:11], off
	s_nop 0
	global_load_dword v10, v[10:11], off offset:64
	s_lshl_b64 s[4:5], s[2:3], 15
	v_lshl_add_u64 v[50:51], v[34:35], 0, s[4:5]
	s_mul_hi_i32 s3, s2, 0x10800
	s_mul_i32 s2, s2, 0x10800
	s_add_u32 s2, s2, s10
	s_addc_u32 s3, s3, 0
	s_add_u32 s2, s2, s6
	s_addc_u32 s3, s3, 0
	s_lshl_b64 s[2:3], s[2:3], 7
	s_waitcnt vmcnt(1)
	v_add_f32_e32 v11, v22, v12
	v_add_f32_e32 v13, v23, v12
	v_add_f32_e32 v14, v24, v12
	v_add_f32_e32 v15, v25, v12
	s_waitcnt vmcnt(0)
	v_add_f32_e32 v16, v18, v10
	v_add_f32_e32 v17, v19, v10
	v_add_f32_e32 v18, v20, v10
	v_add_f32_e32 v19, v21, v10
	v_mul_f32_e32 v20, v11, v11
	v_mul_f32_e32 v21, v13, v13
	v_mul_f32_e32 v22, v14, v14
	v_mul_f32_e32 v23, v15, v15
	v_mul_f32_e32 v24, v16, v16
	v_mul_f32_e32 v25, v17, v17
	v_mul_f32_e32 v46, v18, v18
	v_mul_f32_e32 v47, v19, v19
	v_fmamk_f32 v20, v20, 0xbdd2d3e7, v73
	v_fmamk_f32 v21, v21, 0xbdd2d3e7, v73
	v_fmamk_f32 v22, v22, 0xbdd2d3e7, v73
	v_fmamk_f32 v23, v23, 0xbdd2d3e7, v73
	v_fmamk_f32 v24, v24, 0xbdd2d3e7, v73
	v_fmamk_f32 v25, v25, 0xbdd2d3e7, v73
	v_fmamk_f32 v46, v46, 0xbdd2d3e7, v73
	v_fmamk_f32 v47, v47, 0xbdd2d3e7, v73
	v_mul_f32_e32 v20, v11, v20
	v_mul_f32_e32 v21, v13, v21
	v_mul_f32_e32 v22, v14, v22
	v_mul_f32_e32 v23, v15, v23
	v_mul_f32_e32 v24, v16, v24
	v_mul_f32_e32 v25, v17, v25
	v_mul_f32_e32 v46, v18, v46
	v_mul_f32_e32 v47, v19, v47
	v_exp_f32_e32 v20, v20
	v_add_f32_e32 v6, v6, v12
	v_exp_f32_e32 v21, v21
	v_exp_f32_e32 v22, v22
	v_exp_f32_e32 v23, v23
	v_exp_f32_e32 v24, v24
	v_exp_f32_e32 v25, v25
	v_exp_f32_e32 v46, v46
	v_exp_f32_e32 v47, v47
	v_mul_f32_e32 v48, v6, v6
	v_add_f32_e32 v7, v7, v12
	v_fmamk_f32 v48, v48, 0xbdd2d3e7, v73
	v_mul_f32_e32 v49, v7, v7
	v_mul_f32_e32 v48, v6, v48
	v_add_f32_e32 v20, 1.0, v20
	v_fmamk_f32 v49, v49, 0xbdd2d3e7, v73
	v_exp_f32_e32 v48, v48
	v_add_f32_e32 v21, 1.0, v21
	v_add_f32_e32 v22, 1.0, v22
	v_add_f32_e32 v23, 1.0, v23
	v_add_f32_e32 v24, 1.0, v24
	v_add_f32_e32 v25, 1.0, v25
	v_add_f32_e32 v46, 1.0, v46
	v_add_f32_e32 v47, 1.0, v47
	v_rcp_f32_e32 v20, v20
	v_mul_f32_e32 v49, v7, v49
	v_rcp_f32_e32 v21, v21
	v_rcp_f32_e32 v22, v22
	v_rcp_f32_e32 v23, v23
	v_rcp_f32_e32 v24, v24
	v_rcp_f32_e32 v25, v25
	v_rcp_f32_e32 v46, v46
	v_rcp_f32_e32 v47, v47
	v_exp_f32_e32 v49, v49
	v_add_f32_e32 v48, 1.0, v48
	v_mul_f32_e32 v11, v11, v20
	v_rcp_f32_e32 v48, v48
	v_mul_f32_e32 v13, v13, v21
	v_mul_f32_e32 v14, v14, v22
	v_mul_f32_e32 v15, v15, v23
	v_mul_f32_e32 v16, v16, v24
	v_mul_f32_e32 v17, v17, v25
	v_mul_f32_e32 v18, v18, v46
	v_mul_f32_e32 v19, v19, v47
	v_cvt_pk_bf16_f32 v11, v11, s0
	v_cvt_pk_bf16_f32 v13, v13, s0
	v_cvt_pk_bf16_f32 v14, v14, s0
	v_cvt_pk_bf16_f32 v15, v15, s0
	v_cvt_pk_bf16_f32 v16, v16, s0
	v_cvt_pk_bf16_f32 v17, v17, s0
	v_cvt_pk_bf16_f32 v18, v18, s0
	v_cvt_pk_bf16_f32 v19, v19, s0
	ds_write_b16 v74, v11
	ds_write_b16 v74, v13 offset:528
	ds_write_b16 v74, v14 offset:1056
	ds_write_b16 v74, v15 offset:1584
	ds_write_b16 v74, v16 offset:32
	ds_write_b16 v74, v17 offset:560
	ds_write_b16 v74, v18 offset:1088
	ds_write_b16 v74, v19 offset:1616
	v_add_f32_e32 v11, 1.0, v49
	v_rcp_f32_e32 v11, v11
	v_mul_f32_e32 v6, v6, v48
	v_cvt_pk_bf16_f32 v6, v6, s0
	ds_write_b16 v74, v6 offset:8448
	v_mul_f32_e32 v6, v7, v11
	v_add_f32_e32 v7, v8, v12
	v_mul_f32_e32 v8, v7, v7
	v_fmamk_f32 v8, v8, 0xbdd2d3e7, v73
	v_mul_f32_e32 v8, v7, v8
	v_exp_f32_e32 v8, v8
	v_add_f32_e32 v9, v9, v12
	v_mul_f32_e32 v11, v9, v9
	v_fmamk_f32 v11, v11, 0xbdd2d3e7, v73
	v_add_f32_e32 v8, 1.0, v8
	v_rcp_f32_e32 v8, v8
	v_mul_f32_e32 v11, v9, v11
	v_exp_f32_e32 v11, v11
	v_add_f32_e32 v2, v2, v10
	v_mul_f32_e32 v7, v7, v8
	v_cvt_pk_bf16_f32 v7, v7, s0
	ds_write_b16 v74, v7 offset:9504
	v_mul_f32_e32 v7, v2, v2
	v_cvt_pk_bf16_f32 v6, v6, s0
	v_fmamk_f32 v7, v7, 0xbdd2d3e7, v73
	v_add_f32_e32 v3, v3, v10
	ds_write_b16 v74, v6 offset:8976
	v_add_f32_e32 v6, 1.0, v11
	v_mul_f32_e32 v7, v2, v7
	v_mul_f32_e32 v8, v3, v3
	v_rcp_f32_e32 v6, v6
	v_exp_f32_e32 v7, v7
	v_fmamk_f32 v8, v8, 0xbdd2d3e7, v73
	v_mul_f32_e32 v8, v3, v8
	v_exp_f32_e32 v8, v8
	v_mul_f32_e32 v6, v9, v6
	v_add_f32_e32 v7, 1.0, v7
	v_cvt_pk_bf16_f32 v6, v6, s0
	v_rcp_f32_e32 v7, v7
	ds_write_b16 v74, v6 offset:10032
	v_add_f32_e32 v6, 1.0, v8
	v_rcp_f32_e32 v6, v6
	v_mul_f32_e32 v2, v2, v7
	v_cvt_pk_bf16_f32 v2, v2, s0
	ds_write_b16 v74, v2 offset:8480
	v_mul_f32_e32 v2, v3, v6
	v_add_f32_e32 v3, v4, v10
	v_add_f32_e32 v5, v5, v10
	v_mul_f32_e32 v4, v3, v3
	v_mul_f32_e32 v6, v5, v5
	v_fmamk_f32 v4, v4, 0xbdd2d3e7, v73
	v_fmamk_f32 v6, v6, 0xbdd2d3e7, v73
	v_mul_f32_e32 v4, v3, v4
	v_mul_f32_e32 v6, v5, v6
	v_exp_f32_e32 v4, v4
	v_exp_f32_e32 v6, v6
	v_cvt_pk_bf16_f32 v2, v2, s0
	ds_write_b16 v74, v2 offset:9008
	v_add_f32_e32 v4, 1.0, v4
	v_add_f32_e32 v2, 1.0, v6
	v_rcp_f32_e32 v4, v4
	v_rcp_f32_e32 v2, v2
	v_mul_f32_e32 v3, v3, v4
	v_mul_f32_e32 v2, v5, v2
	v_cvt_pk_bf16_f32 v3, v3, s0
	v_cvt_pk_bf16_f32 v2, v2, s0
	ds_write_b16 v74, v3 offset:9536
	ds_write_b16 v74, v2 offset:10064
	s_waitcnt lgkmcnt(0)
	s_barrier
; #define LAS __attribute__((address_space(3)))
; DI unsigned pk2(float lo, float hi) { f32x2 v = {lo, hi}; bf16x2_t b = __builtin_convertvector(v, bf16x2_t); return __builtin_bit_cast(unsigned, b); }
; DI void pcmp_unit(const Args& a, LAS unsigned char* lds, int kind, int seq, int quarter, int wave, int lane) {
;     ...
;     {
;         const int mt = wave >> 2, nt = wave & 3; const bf16_t* w2 = (const bf16_t*)(ws + WS_W2C_T) + (size_t)kind * 64 * 256 + (size_t)fr * 256 + 8 * fq;
;         bf16_t* kc = (bf16_t*)(ws + WS_KC) + ((size_t)kind * AROWS + arow0 + 16 * mt) * 64;
;         f32x4 c = {0.f, 0.f, 0.f, 0.f};
; #pragma unroll
;         for (int ks = 0; ks < 8; ++ks) { const bf16x8 af = *(const LAS bf16x8*)(G + (16 * mt + fr) * 264 + 32 * ks + 8 * fq); const bf16x8 bfr = *(const bf16x8*)(w2 + (size_t)nt * 16 * 256 + 32 * ks);
;             c = __builtin_amdgcn_mfma_f32_16x16x32_bf16(af, bfr, c, 0, 0, 0); }
; #pragma unroll
;         for (int j = 0; j < 4; ++j) kc[(size_t)(4 * fq + j) * 64 + nt * 16 + fr] = (bf16_t)(pk2(c[j], 0.f) & 0xffffu);
;     }
;     __syncthreads();
; }
	global_load_dwordx4 v[2:5], v[50:51], off
	global_load_dwordx4 v[6:9], v[50:51], off offset:64
	global_load_dwordx4 v[10:13], v[50:51], off offset:128
	global_load_dwordx4 v[14:17], v[50:51], off offset:192
	global_load_dwordx4 v[18:21], v[50:51], off offset:256
	global_load_dwordx4 v[22:25], v[50:51], off offset:320
	global_load_dwordx4 v[46:49], v[50:51], off offset:384
	global_load_dwordx4 v[76:79], v[50:51], off offset:448
	ds_read_b128 v[80:83], v75
	ds_read_b128 v[84:87], v75 offset:64
	s_waitcnt vmcnt(7) lgkmcnt(1)
	v_mfma_f32_16x16x32_bf16 v[2:5], v[80:83], v[2:5], 0
	ds_read_b128 v[80:83], v75 offset:128
	s_waitcnt vmcnt(6) lgkmcnt(1)
	v_mfma_f32_16x16x32_bf16 v[2:5], v[84:87], v[6:9], v[2:5]
	ds_read_b128 v[6:9], v75 offset:192
	s_waitcnt vmcnt(5) lgkmcnt(1)
	v_mfma_f32_16x16x32_bf16 v[2:5], v[80:83], v[10:13], v[2:5]
	ds_read_b128 v[10:13], v75 offset:256
	s_waitcnt vmcnt(4) lgkmcnt(1)
	v_mfma_f32_16x16x32_bf16 v[2:5], v[6:9], v[14:17], v[2:5]
	ds_read_b128 v[6:9], v75 offset:320
	ds_read_b128 v[14:17], v75 offset:384
	s_waitcnt vmcnt(3) lgkmcnt(2)
	v_mfma_f32_16x16x32_bf16 v[2:5], v[10:13], v[18:21], v[2:5]
	ds_read_b128 v[10:13], v75 offset:448
	s_waitcnt vmcnt(2) lgkmcnt(2)
	v_mfma_f32_16x16x32_bf16 v[2:5], v[6:9], v[22:25], v[2:5]
	v_lshl_add_u64 v[6:7], v[36:37], 0, s[2:3]
	s_waitcnt vmcnt(1) lgkmcnt(1)
	v_mfma_f32_16x16x32_bf16 v[2:5], v[14:17], v[46:49], v[2:5]
	s_waitcnt vmcnt(0) lgkmcnt(0)
	v_mfma_f32_16x16x32_bf16 v[2:5], v[10:13], v[76:79], v[2:5]
	s_nop 7
	v_cvt_pk_bf16_f32 v2, v2, s0
	v_cvt_pk_bf16_f32 v3, v3, s0
	v_cvt_pk_bf16_f32 v4, v4, s0
	v_cvt_pk_bf16_f32 v5, v5, s0
	global_store_short v[6:7], v2, off
	global_store_short v[6:7], v3, off offset:128
	global_store_short v[6:7], v4, off offset:256
	global_store_short v[6:7], v5, off offset:384
	s_barrier
	s_barrier
	s_and_saveexec_b64 s[2:3], s[0:1]
	s_cbranch_execz .LBB0_1300
	s_mov_b64 s[6:7], exec
	v_mbcnt_lo_u32_b32 v2, s6, 0
	v_mbcnt_hi_u32_b32 v2, s7, v2
	v_cmp_eq_u32_e32 vcc, 0, v2
	s_and_saveexec_b64 s[4:5], vcc
	s_cbranch_execz .LBB0_1299
	s_bcnt1_i32_b64 s6, s[6:7]
	v_mov_b32_e32 v3, s6
	v_mov_b32_e32 v3, v255
	s_branch .LBB0_1299

; DI void mblk_unit(const Args& a, LAS unsigned char* lds, int b, int h, int J) {
;     ...
;     __syncthreads();
;     NR[npart * 128 + ndk] = nacc;
;     __syncthreads();
;     if (tid < 128) ((float*)(ws + WS_DN))[(seq * 8 + J) * 128 + tid] = (NR[tid] + NR[128 + tid]) + (NR[256 + tid] + NR[384 + tid]);
;     __syncthreads();
; }
.LBB0_1322:
	s_or_b64 exec, exec, s[2:3]
	s_barrier
	s_barrier
	s_and_saveexec_b64 s[2:3], s[0:1]
	s_cbranch_execz .LBB0_1311
	s_mov_b64 s[6:7], exec
	v_mbcnt_lo_u32_b32 v2, s6, 0
	v_mbcnt_hi_u32_b32 v2, s7, v2
	v_cmp_eq_u32_e32 vcc, 0, v2
	s_and_saveexec_b64 s[4:5], vcc
	s_cbranch_execz .LBB0_1310
	s_bcnt1_i32_b64 s6, s[6:7]
	v_mov_b32_e32 v3, s6
	v_mov_b32_e32 v3, v255
	s_branch .LBB0_1310

; DI bf16x8 pack8(f32x4 a, f32x4 b) { u32x4 p; p.x = pk2(a.x, a.y); p.y = pk2(a.z, a.w); p.z = pk2(b.x, b.y); p.w = pk2(b.z, b.w); return __builtin_bit_cast(bf16x8, p); }
; DI void w2_compute(const Args& a, LAS unsigned char* lds, int task, int lane, const u32x4 (&x0)[8], const u32x4 (&x1)[8]) {
;     ...
;     const int kind = task / (AROWS_S / 16), row0 = AROWS_P + (task % (AROWS_S / 16)) * 16;
;     const float* cb = (const float*)(ws + WS_CBIAS) + kind * 256 + 8 * fq;
;     bf16x8 af[8];
; #pragma unroll
;     for (int ks = 0; ks < 8; ++ks) { const f32x4 c0 = *(const f32x4*)(cb + 32 * ks), c1 = *(const f32x4*)(cb + 32 * ks + 4);
;         f32x4 g0, g1;
;         g0.x = gelu_tanh(bf2f(x0[ks].x & 0xffffu) + bf2f(x1[ks].x & 0xffffu) + c0.x); g0.y = gelu_tanh(bf2f(x0[ks].x >> 16) + bf2f(x1[ks].x >> 16) + c0.y);
;         g0.z = gelu_tanh(bf2f(x0[ks].y & 0xffffu) + bf2f(x1[ks].y & 0xffffu) + c0.z); g0.w = gelu_tanh(bf2f(x0[ks].y >> 16) + bf2f(x1[ks].y >> 16) + c0.w);
;         g1.x = gelu_tanh(bf2f(x0[ks].z & 0xffffu) + bf2f(x1[ks].z & 0xffffu) + c1.x); g1.y = gelu_tanh(bf2f(x0[ks].z >> 16) + bf2f(x1[ks].z >> 16) + c1.y);
;         g1.z = gelu_tanh(bf2f(x0[ks].w & 0xffffu) + bf2f(x1[ks].w & 0xffffu) + c1.z); g1.w = gelu_tanh(bf2f(x0[ks].w >> 16) + bf2f(x1[ks].w >> 16) + c1.w);
;         af[ks] = pack8(g0, g1); }
.LBB0_1382:
	s_or_b64 exec, exec, s[12:13]
	s_lshl_b32 s12, s10, 8
	s_ashr_i32 s13, s12, 31
	v_lshl_add_u64 v[112:113], s[12:13], 2, v[106:107]
	global_load_dwordx4 v[154:157], v[112:113], off
	global_load_dwordx4 v[160:163], v[112:113], off offset:16
	global_load_dwordx4 v[164:167], v[112:113], off offset:128
	global_load_dwordx4 v[168:171], v[112:113], off offset:144
	s_waitcnt vmcnt(17)
	v_lshlrev_b32_e32 v100, 16, v98
	v_and_b32_e32 v101, 0xffff0000, v98
	v_lshlrev_b32_e32 v98, 16, v99
	v_and_b32_e32 v99, 0xffff0000, v99
	s_waitcnt vmcnt(16)
	v_lshlrev_b32_e32 v172, 16, v92
	v_and_b32_e32 v173, 0xffff0000, v92
	v_pk_add_f32 v[176:177], v[100:101], 0 op_sel_hi:[1,0]
	v_pk_add_f32 v[178:179], v[98:99], 0 op_sel_hi:[1,0]
	v_pk_add_f32 v[180:181], v[172:173], 0 op_sel_hi:[1,0]
	global_load_dwordx4 v[98:101], v[112:113], off offset:272
	global_load_dwordx4 v[172:175], v[112:113], off offset:256
	v_lshlrev_b32_e32 v90, 16, v96
	v_and_b32_e32 v91, 0xffff0000, v96
	v_lshlrev_b32_e32 v96, 16, v97
	v_and_b32_e32 v97, 0xffff0000, v97
	v_lshlrev_b32_e32 v92, 16, v93
	v_and_b32_e32 v93, 0xffff0000, v93
	v_pk_add_f32 v[90:91], v[90:91], 0 op_sel_hi:[1,0]
	v_pk_add_f32 v[96:97], v[96:97], 0 op_sel_hi:[1,0]
	v_pk_add_f32 v[92:93], v[92:93], 0 op_sel_hi:[1,0]
	s_lshl_b32 s9, s10, 15
	s_add_i32 s9, s34, s9
	s_addk_i32 s37, 0x800
	s_ashr_i32 s12, s37, 31
	s_waitcnt vmcnt(5)
	v_pk_add_f32 v[90:91], v[90:91], v[154:155]
	v_pk_add_f32 v[96:97], v[96:97], v[156:157]
	s_waitcnt vmcnt(4)
	v_pk_add_f32 v[154:155], v[176:177], v[160:161]
	v_pk_add_f32 v[156:157], v[178:179], v[162:163]
	s_waitcnt vmcnt(3)
	v_pk_add_f32 v[160:161], v[180:181], v[164:165]
	v_pk_add_f32 v[164:165], v[92:93], v[166:167]
	v_pk_mul_f32 v[92:93], v[90:91], v[90:91]
	v_pk_mul_f32 v[162:163], v[96:97], v[96:97]
	v_pk_mul_f32 v[166:167], v[154:155], v[154:155]
	v_pk_mul_f32 v[176:177], v[156:157], v[156:157]
	v_fmamk_f32 v92, v92, 0xbdd2d3e7, v153
	v_fmamk_f32 v93, v93, 0xbdd2d3e7, v153
	v_fmamk_f32 v102, v162, 0xbdd2d3e7, v153
	v_fmamk_f32 v111, v163, 0xbdd2d3e7, v153
	v_fmamk_f32 v162, v166, 0xbdd2d3e7, v153
	v_fmamk_f32 v163, v167, 0xbdd2d3e7, v153
	v_fmamk_f32 v166, v176, 0xbdd2d3e7, v153
	v_fmamk_f32 v167, v177, 0xbdd2d3e7, v153
	v_mul_f32_e32 v92, v90, v92
	v_mul_f32_e32 v93, v91, v93
	v_mul_f32_e32 v102, v96, v102
	v_mul_f32_e32 v111, v97, v111
	v_mul_f32_e32 v162, v154, v162
	v_mul_f32_e32 v163, v155, v163
	v_mul_f32_e32 v166, v156, v166
	v_mul_f32_e32 v167, v157, v167
	v_exp_f32_e32 v92, v92
	v_exp_f32_e32 v93, v93
	v_exp_f32_e32 v102, v102
	v_exp_f32_e32 v111, v111
	v_exp_f32_e32 v162, v162
	v_exp_f32_e32 v163, v163
	v_pk_mul_f32 v[178:179], v[160:161], v[160:161]
	v_exp_f32_e32 v166, v166
	v_exp_f32_e32 v167, v167
	v_fmamk_f32 v176, v178, 0xbdd2d3e7, v153
	v_fmamk_f32 v177, v179, 0xbdd2d3e7, v153
	v_mul_f32_e32 v176, v160, v176
	v_mul_f32_e32 v177, v161, v177
	v_exp_f32_e32 v176, v176
	v_exp_f32_e32 v177, v177
	v_add_f32_e32 v92, 1.0, v92
	v_add_f32_e32 v93, 1.0, v93
	v_add_f32_e32 v102, 1.0, v102
	v_add_f32_e32 v111, 1.0, v111
	v_add_f32_e32 v178, 1.0, v162
	v_add_f32_e32 v179, 1.0, v163
	v_add_f32_e32 v182, 1.0, v166
	v_add_f32_e32 v183, 1.0, v167
	v_rcp_f32_e32 v92, v92
	v_rcp_f32_e32 v93, v93
	v_rcp_f32_e32 v162, v102
	v_rcp_f32_e32 v163, v111
	v_rcp_f32_e32 v166, v178
	v_rcp_f32_e32 v167, v179
	v_pk_mul_f32 v[180:181], v[164:165], v[164:165]
	v_add_f32_e32 v184, 1.0, v176
	v_add_f32_e32 v185, 1.0, v177
	v_rcp_f32_e32 v176, v182
	v_rcp_f32_e32 v177, v183
	v_fmamk_f32 v180, v180, 0xbdd2d3e7, v153
	v_pk_mul_f32 v[90:91], v[90:91], v[92:93]
	v_pk_mul_f32 v[92:93], v[96:97], v[162:163]
	v_pk_mul_f32 v[96:97], v[154:155], v[166:167]
	v_cvt_pk_bf16_f32 v90, v90, v91
	v_cvt_pk_bf16_f32 v91, v92, v93
	v_cvt_pk_bf16_f32 v92, v96, v97
	v_mul_f32_e32 v96, v164, v180
	v_exp_f32_e32 v102, v96
	v_fmamk_f32 v96, v181, 0xbdd2d3e7, v153
	v_pk_mul_f32 v[154:155], v[156:157], v[176:177]
	v_mul_f32_e32 v96, v165, v96
	v_cvt_pk_bf16_f32 v93, v154, v155
	v_exp_f32_e32 v111, v96
	v_lshlrev_b32_e32 v154, 16, v94
	v_and_b32_e32 v155, 0xffff0000, v94
	v_pk_add_f32 v[154:155], v[154:155], 0 op_sel_hi:[1,0]
	v_add_f32_e32 v102, 1.0, v102
	s_waitcnt vmcnt(2)
	v_pk_add_f32 v[168:169], v[154:155], v[168:169]
	v_rcp_f32_e32 v166, v102
	v_pk_mul_f32 v[154:155], v[168:169], v[168:169]
	v_add_f32_e32 v102, 1.0, v111
	v_fmamk_f32 v94, v154, 0xbdd2d3e7, v153
	v_fmamk_f32 v111, v155, 0xbdd2d3e7, v153
	v_lshlrev_b32_e32 v154, 16, v95
	v_and_b32_e32 v155, 0xffff0000, v95
	v_mul_f32_e32 v111, v169, v111
	v_pk_add_f32 v[154:155], v[154:155], 0 op_sel_hi:[1,0]
	v_exp_f32_e32 v111, v111
	v_pk_add_f32 v[170:171], v[154:155], v[170:171]
	v_rcp_f32_e32 v167, v102
	v_pk_mul_f32 v[154:155], v[170:171], v[170:171]
	v_add_f32_e32 v102, 1.0, v111
	v_fmamk_f32 v95, v154, 0xbdd2d3e7, v153
	v_mul_f32_e32 v95, v170, v95
	v_exp_f32_e32 v111, v95
	v_fmamk_f32 v95, v155, 0xbdd2d3e7, v153
	v_mul_f32_e32 v95, v171, v95
	v_rcp_f32_e32 v178, v184
	v_rcp_f32_e32 v179, v185
	v_exp_f32_e32 v154, v95
	v_rcp_f32_e32 v95, v102
	v_add_f32_e32 v102, 1.0, v111
	v_pk_mul_f32 v[96:97], v[160:161], v[178:179]
	v_rcp_f32_e32 v176, v102
	v_add_f32_e32 v102, 1.0, v154
	global_load_dwordx4 v[154:157], v[112:113], off offset:400
	global_load_dwordx4 v[160:163], v[112:113], off offset:384
	v_mul_f32_e32 v94, v168, v94
	v_exp_f32_e32 v94, v94
	v_pk_mul_f32 v[164:165], v[164:165], v[166:167]
	v_rcp_f32_e32 v177, v102
	v_add_f32_e32 v94, 1.0, v94
	v_rcp_f32_e32 v94, v94
	s_nop 0
	v_pk_mul_f32 v[166:167], v[168:169], v[94:95]
	v_cvt_pk_bf16_f32 v95, v164, v165
	v_lshlrev_b32_e32 v164, 16, v86
	v_and_b32_e32 v165, 0xffff0000, v86
	v_pk_add_f32 v[164:165], v[164:165], 0 op_sel_hi:[1,0]
	v_cvt_pk_bf16_f32 v94, v96, v97
	s_waitcnt vmcnt(2)
; DI bf16x8 pack8(f32x4 a, f32x4 b) { u32x4 p; p.x = pk2(a.x, a.y); p.y = pk2(a.z, a.w); p.z = pk2(b.x, b.y); p.w = pk2(b.z, b.w); return __builtin_bit_cast(bf16x8, p); }
; DI void w2_compute(const Args& a, LAS unsigned char* lds, int task, int lane, const u32x4 (&x0)[8], const u32x4 (&x1)[8]) {
;     ...
;     for (int ks = 0; ks < 8; ++ks) { const f32x4 c0 = *(const f32x4*)(cb + 32 * ks), c1 = *(const f32x4*)(cb + 32 * ks + 4);
;         f32x4 g0, g1;
;         g0.x = gelu_tanh(bf2f(x0[ks].x & 0xffffu) + bf2f(x1[ks].x & 0xffffu) + c0.x); g0.y = gelu_tanh(bf2f(x0[ks].x >> 16) + bf2f(x1[ks].x >> 16) + c0.y);
;         g0.z = gelu_tanh(bf2f(x0[ks].y & 0xffffu) + bf2f(x1[ks].y & 0xffffu) + c0.z); g0.w = gelu_tanh(bf2f(x0[ks].y >> 16) + bf2f(x1[ks].y >> 16) + c0.w);
;         g1.x = gelu_tanh(bf2f(x0[ks].z & 0xffffu) + bf2f(x1[ks].z & 0xffffu) + c1.x); g1.y = gelu_tanh(bf2f(x0[ks].z >> 16) + bf2f(x1[ks].z >> 16) + c1.y);
;         g1.z = gelu_tanh(bf2f(x0[ks].w & 0xffffu) + bf2f(x1[ks].w & 0xffffu) + c1.z); g1.w = gelu_tanh(bf2f(x0[ks].w >> 16) + bf2f(x1[ks].w >> 16) + c1.w);
;         af[ks] = pack8(g0, g1); }
	v_pk_add_f32 v[164:165], v[164:165], v[172:173]
	v_cvt_pk_bf16_f32 v96, v166, v167
	v_pk_mul_f32 v[166:167], v[164:165], v[164:165]
	v_pk_mul_f32 v[168:169], v[170:171], v[176:177]
	v_fmamk_f32 v86, v166, 0xbdd2d3e7, v153
	v_mul_f32_e32 v86, v164, v86
	v_fmamk_f32 v97, v167, 0xbdd2d3e7, v153
	v_exp_f32_e32 v86, v86
	v_mul_f32_e32 v97, v165, v97
	v_exp_f32_e32 v102, v97
	v_cvt_pk_bf16_f32 v97, v168, v169
	v_add_f32_e32 v86, 1.0, v86
	v_rcp_f32_e32 v166, v86
	v_add_f32_e32 v86, 1.0, v102
	v_rcp_f32_e32 v167, v86
	v_lshlrev_b32_e32 v86, 16, v87
	v_and_b32_e32 v87, 0xffff0000, v87
	v_pk_add_f32 v[86:87], v[86:87], 0 op_sel_hi:[1,0]
	s_nop 0
	v_pk_add_f32 v[86:87], v[86:87], v[174:175]
	s_nop 0
	v_pk_mul_f32 v[168:169], v[86:87], v[86:87]
	s_nop 0
	v_fmamk_f32 v102, v168, 0xbdd2d3e7, v153
	v_fmamk_f32 v111, v169, 0xbdd2d3e7, v153
	v_pk_mul_f32 v[168:169], v[164:165], v[166:167]
	v_lshlrev_b32_e32 v164, 16, v88
	v_and_b32_e32 v165, 0xffff0000, v88
	v_pk_add_f32 v[164:165], v[164:165], 0 op_sel_hi:[1,0]
	v_mul_f32_e32 v102, v86, v102
	v_pk_add_f32 v[172:173], v[164:165], v[98:99]
	v_exp_f32_e32 v102, v102
	v_pk_mul_f32 v[98:99], v[172:173], v[172:173]
	v_mul_f32_e32 v111, v87, v111
	v_fmamk_f32 v88, v98, 0xbdd2d3e7, v153
	v_fmamk_f32 v98, v99, 0xbdd2d3e7, v153
	v_exp_f32_e32 v111, v111
	v_mul_f32_e32 v98, v173, v98
	v_exp_f32_e32 v98, v98
	v_add_f32_e32 v102, 1.0, v102
	v_rcp_f32_e32 v170, v102
	v_add_f32_e32 v102, 1.0, v111
	v_rcp_f32_e32 v171, v102
	v_add_f32_e32 v102, 1.0, v98
	v_lshlrev_b32_e32 v98, 16, v89
	v_and_b32_e32 v99, 0xffff0000, v89
	v_pk_add_f32 v[98:99], v[98:99], 0 op_sel_hi:[1,0]
	v_mul_f32_e32 v88, v172, v88
	v_pk_add_f32 v[174:175], v[98:99], v[100:101]
	v_exp_f32_e32 v88, v88
	v_pk_mul_f32 v[98:99], v[174:175], v[174:175]
	v_pk_mul_f32 v[170:171], v[86:87], v[170:171]
	v_fmamk_f32 v89, v98, 0xbdd2d3e7, v153
	v_mul_f32_e32 v89, v174, v89
	v_exp_f32_e32 v98, v89
	v_fmamk_f32 v89, v99, 0xbdd2d3e7, v153
	v_mul_f32_e32 v89, v175, v89
	v_exp_f32_e32 v99, v89
	v_add_f32_e32 v98, 1.0, v98
	v_rcp_f32_e32 v176, v98
	v_add_f32_e32 v88, 1.0, v88
	v_add_f32_e32 v98, 1.0, v99
	v_rcp_f32_e32 v177, v98
	global_load_dwordx4 v[98:101], v[112:113], off offset:528
	global_load_dwordx4 v[164:167], v[112:113], off offset:512
	v_rcp_f32_e32 v88, v88
	v_rcp_f32_e32 v89, v102
	v_cvt_pk_bf16_f32 v86, v168, v169
	v_lshlrev_b32_e32 v168, 16, v82
	v_and_b32_e32 v169, 0xffff0000, v82
	v_pk_add_f32 v[168:169], v[168:169], 0 op_sel_hi:[1,0]
	v_pk_mul_f32 v[88:89], v[172:173], v[88:89]
	s_waitcnt vmcnt(2)
	v_pk_add_f32 v[160:161], v[168:169], v[160:161]
	v_cvt_pk_bf16_f32 v88, v88, v89
	v_pk_mul_f32 v[168:169], v[160:161], v[160:161]
	v_pk_mul_f32 v[172:173], v[174:175], v[176:177]
	v_fmamk_f32 v82, v168, 0xbdd2d3e7, v153
	v_mul_f32_e32 v82, v160, v82
	v_fmamk_f32 v89, v169, 0xbdd2d3e7, v153
	v_exp_f32_e32 v82, v82
	v_mul_f32_e32 v89, v161, v89
	v_exp_f32_e32 v102, v89
	v_cvt_pk_bf16_f32 v89, v172, v173
	v_add_f32_e32 v82, 1.0, v82
	v_rcp_f32_e32 v168, v82
	v_add_f32_e32 v82, 1.0, v102
	v_rcp_f32_e32 v169, v82
	v_lshlrev_b32_e32 v82, 16, v83
	v_and_b32_e32 v83, 0xffff0000, v83
	v_pk_add_f32 v[82:83], v[82:83], 0 op_sel_hi:[1,0]
	v_pk_mul_f32 v[168:169], v[160:161], v[168:169]
	v_pk_add_f32 v[82:83], v[82:83], v[162:163]
	v_lshlrev_b32_e32 v160, 16, v84
	v_pk_mul_f32 v[162:163], v[82:83], v[82:83]
	v_and_b32_e32 v161, 0xffff0000, v84
	v_fmamk_f32 v102, v162, 0xbdd2d3e7, v153
	v_mul_f32_e32 v102, v82, v102
	v_fmamk_f32 v111, v163, 0xbdd2d3e7, v153
	v_exp_f32_e32 v102, v102
	v_mul_f32_e32 v111, v83, v111
	v_exp_f32_e32 v111, v111
	v_pk_add_f32 v[160:161], v[160:161], 0 op_sel_hi:[1,0]
	v_add_f32_e32 v102, 1.0, v102
	v_pk_add_f32 v[172:173], v[160:161], v[154:155]
	v_cvt_pk_bf16_f32 v87, v170, v171
	v_pk_mul_f32 v[154:155], v[172:173], v[172:173]
	v_rcp_f32_e32 v170, v102
	v_add_f32_e32 v102, 1.0, v111
	v_fmamk_f32 v84, v154, 0xbdd2d3e7, v153
	v_fmamk_f32 v111, v155, 0xbdd2d3e7, v153
	v_lshlrev_b32_e32 v154, 16, v85
	v_and_b32_e32 v155, 0xffff0000, v85
	v_mul_f32_e32 v111, v173, v111
	v_pk_add_f32 v[154:155], v[154:155], 0 op_sel_hi:[1,0]
	v_exp_f32_e32 v111, v111
	v_pk_add_f32 v[174:175], v[154:155], v[156:157]
	v_rcp_f32_e32 v171, v102
	v_pk_mul_f32 v[154:155], v[174:175], v[174:175]
	v_add_f32_e32 v102, 1.0, v111
	v_fmamk_f32 v85, v154, 0xbdd2d3e7, v153
	v_mul_f32_e32 v85, v174, v85
	v_exp_f32_e32 v111, v85
	v_fmamk_f32 v85, v155, 0xbdd2d3e7, v153
	v_mul_f32_e32 v85, v175, v85
	v_exp_f32_e32 v154, v85
	v_rcp_f32_e32 v85, v102
	v_add_f32_e32 v102, 1.0, v111
	v_rcp_f32_e32 v176, v102
	v_add_f32_e32 v102, 1.0, v154
	global_load_dwordx4 v[154:157], v[112:113], off offset:656
	global_load_dwordx4 v[160:163], v[112:113], off offset:640
	v_mul_f32_e32 v84, v172, v84
	v_exp_f32_e32 v84, v84
	v_pk_mul_f32 v[170:171], v[82:83], v[170:171]
	v_cvt_pk_bf16_f32 v82, v168, v169
	v_lshlrev_b32_e32 v168, 16, v78
	v_add_f32_e32 v84, 1.0, v84
	v_rcp_f32_e32 v84, v84
	v_and_b32_e32 v169, 0xffff0000, v78
	v_pk_add_f32 v[168:169], v[168:169], 0 op_sel_hi:[1,0]
	v_rcp_f32_e32 v177, v102
	v_pk_mul_f32 v[84:85], v[172:173], v[84:85]
	v_cvt_pk_bf16_f32 v83, v170, v171
	v_cvt_pk_bf16_f32 v84, v84, v85
	v_pk_mul_f32 v[172:173], v[174:175], v[176:177]
	s_waitcnt vmcnt(2)
; DI bf16x8 pack8(f32x4 a, f32x4 b) { u32x4 p; p.x = pk2(a.x, a.y); p.y = pk2(a.z, a.w); p.z = pk2(b.x, b.y); p.w = pk2(b.z, b.w); return __builtin_bit_cast(bf16x8, p); }
; DI float gelu_tanh(float x) { const float x2 = x * x; const float ny = x * (x2 * (-0.044715f * 1.5957691216057308f * 1.4426950408889634f) - 1.5957691216057308f * 1.4426950408889634f);
;     return x * __builtin_amdgcn_rcpf(1.f + __builtin_amdgcn_exp2f(ny)); }
; DI void w2_compute(const Args& a, LAS unsigned char* lds, int task, int lane, const u32x4 (&x0)[8], const u32x4 (&x1)[8]) {
;     ...
;     for (int ks = 0; ks < 8; ++ks) { const f32x4 c0 = *(const f32x4*)(cb + 32 * ks), c1 = *(const f32x4*)(cb + 32 * ks + 4);
;         f32x4 g0, g1;
;         g0.x = gelu_tanh(bf2f(x0[ks].x & 0xffffu) + bf2f(x1[ks].x & 0xffffu) + c0.x); g0.y = gelu_tanh(bf2f(x0[ks].x >> 16) + bf2f(x1[ks].x >> 16) + c0.y);
;         g0.z = gelu_tanh(bf2f(x0[ks].y & 0xffffu) + bf2f(x1[ks].y & 0xffffu) + c0.z); g0.w = gelu_tanh(bf2f(x0[ks].y >> 16) + bf2f(x1[ks].y >> 16) + c0.w);
;         g1.x = gelu_tanh(bf2f(x0[ks].z & 0xffffu) + bf2f(x1[ks].z & 0xffffu) + c1.x); g1.y = gelu_tanh(bf2f(x0[ks].z >> 16) + bf2f(x1[ks].z >> 16) + c1.y);
;         g1.z = gelu_tanh(bf2f(x0[ks].w & 0xffffu) + bf2f(x1[ks].w & 0xffffu) + c1.z); g1.w = gelu_tanh(bf2f(x0[ks].w >> 16) + bf2f(x1[ks].w >> 16) + c1.w);
;         af[ks] = pack8(g0, g1); }
	v_pk_add_f32 v[164:165], v[168:169], v[164:165]
	s_nop 0
	v_pk_mul_f32 v[168:169], v[164:165], v[164:165]
	s_nop 0
	v_fmamk_f32 v78, v168, 0xbdd2d3e7, v153
	v_mul_f32_e32 v78, v164, v78
	v_fmamk_f32 v85, v169, 0xbdd2d3e7, v153
	v_exp_f32_e32 v78, v78
	v_mul_f32_e32 v85, v165, v85
	v_exp_f32_e32 v102, v85
	v_cvt_pk_bf16_f32 v85, v172, v173
	v_add_f32_e32 v78, 1.0, v78
	v_rcp_f32_e32 v168, v78
	v_add_f32_e32 v78, 1.0, v102
	v_rcp_f32_e32 v169, v78
	v_lshlrev_b32_e32 v78, 16, v79
	v_and_b32_e32 v79, 0xffff0000, v79
	v_pk_add_f32 v[78:79], v[78:79], 0 op_sel_hi:[1,0]
	v_pk_mul_f32 v[168:169], v[164:165], v[168:169]
	v_pk_add_f32 v[78:79], v[78:79], v[166:167]
	v_lshlrev_b32_e32 v164, 16, v80
	v_and_b32_e32 v165, 0xffff0000, v80
	v_pk_mul_f32 v[166:167], v[78:79], v[78:79]
	v_pk_add_f32 v[164:165], v[164:165], 0 op_sel_hi:[1,0]
	v_fmamk_f32 v102, v166, 0xbdd2d3e7, v153
	v_pk_add_f32 v[172:173], v[164:165], v[98:99]
	v_mul_f32_e32 v102, v78, v102
	v_fmamk_f32 v111, v167, 0xbdd2d3e7, v153
	v_pk_mul_f32 v[98:99], v[172:173], v[172:173]
	v_exp_f32_e32 v102, v102
	v_mul_f32_e32 v111, v79, v111
	v_fmamk_f32 v80, v98, 0xbdd2d3e7, v153
	v_fmamk_f32 v98, v99, 0xbdd2d3e7, v153
	v_exp_f32_e32 v111, v111
	v_mul_f32_e32 v98, v173, v98
	v_exp_f32_e32 v98, v98
	v_add_f32_e32 v102, 1.0, v102
	v_rcp_f32_e32 v170, v102
	v_add_f32_e32 v102, 1.0, v111
	v_rcp_f32_e32 v171, v102
	v_add_f32_e32 v102, 1.0, v98
	v_lshlrev_b32_e32 v98, 16, v81
	v_and_b32_e32 v99, 0xffff0000, v81
	v_pk_add_f32 v[98:99], v[98:99], 0 op_sel_hi:[1,0]
	v_mul_f32_e32 v80, v172, v80
	v_pk_add_f32 v[174:175], v[98:99], v[100:101]
	v_exp_f32_e32 v80, v80
	v_pk_mul_f32 v[98:99], v[174:175], v[174:175]
	v_pk_mul_f32 v[170:171], v[78:79], v[170:171]
	v_fmamk_f32 v81, v98, 0xbdd2d3e7, v153
	v_mul_f32_e32 v81, v174, v81
	v_exp_f32_e32 v98, v81
	v_fmamk_f32 v81, v99, 0xbdd2d3e7, v153
	v_mul_f32_e32 v81, v175, v81
	v_exp_f32_e32 v99, v81
	v_add_f32_e32 v80, 1.0, v80
	v_rcp_f32_e32 v80, v80
	v_rcp_f32_e32 v81, v102
	v_add_f32_e32 v98, 1.0, v98
	v_rcp_f32_e32 v176, v98
	v_add_f32_e32 v98, 1.0, v99
	v_cvt_pk_bf16_f32 v78, v168, v169
	v_lshlrev_b32_e32 v168, 16, v74
	v_and_b32_e32 v169, 0xffff0000, v74
	v_rcp_f32_e32 v177, v98
	global_load_dwordx4 v[98:101], v[112:113], off offset:784
	global_load_dwordx4 v[164:167], v[112:113], off offset:768
	v_pk_add_f32 v[168:169], v[168:169], 0 op_sel_hi:[1,0]
	v_pk_mul_f32 v[80:81], v[172:173], v[80:81]
	s_waitcnt vmcnt(2)
	v_pk_add_f32 v[168:169], v[168:169], v[160:161]
	v_cvt_pk_bf16_f32 v80, v80, v81
	v_pk_mul_f32 v[160:161], v[168:169], v[168:169]
	v_cvt_pk_bf16_f32 v79, v170, v171
	v_fmamk_f32 v74, v160, 0xbdd2d3e7, v153
	v_fmamk_f32 v81, v161, 0xbdd2d3e7, v153
	v_lshlrev_b32_e32 v160, 16, v75
	v_and_b32_e32 v161, 0xffff0000, v75
	v_pk_add_f32 v[160:161], v[160:161], 0 op_sel_hi:[1,0]
	v_mul_f32_e32 v81, v169, v81
	v_pk_add_f32 v[170:171], v[160:161], v[162:163]
	v_exp_f32_e32 v102, v81
	v_pk_mul_f32 v[160:161], v[170:171], v[170:171]
	v_pk_mul_f32 v[172:173], v[174:175], v[176:177]
	v_fmamk_f32 v75, v160, 0xbdd2d3e7, v153
	v_mul_f32_e32 v75, v170, v75
	v_exp_f32_e32 v111, v75
	v_fmamk_f32 v75, v161, 0xbdd2d3e7, v153
	v_mul_f32_e32 v75, v171, v75
	v_exp_f32_e32 v160, v75
	v_add_f32_e32 v102, 1.0, v102
	v_rcp_f32_e32 v75, v102
	v_add_f32_e32 v102, 1.0, v111
	v_cvt_pk_bf16_f32 v81, v172, v173
	v_rcp_f32_e32 v172, v102
	v_add_f32_e32 v102, 1.0, v160
	v_lshlrev_b32_e32 v160, 16, v76
	v_and_b32_e32 v161, 0xffff0000, v76
	v_pk_add_f32 v[160:161], v[160:161], 0 op_sel_hi:[1,0]
	v_rcp_f32_e32 v173, v102
	v_pk_add_f32 v[174:175], v[160:161], v[154:155]
	v_mul_f32_e32 v74, v168, v74
	v_pk_mul_f32 v[154:155], v[174:175], v[174:175]
	v_exp_f32_e32 v74, v74
	v_fmamk_f32 v76, v154, 0xbdd2d3e7, v153
	v_fmamk_f32 v111, v155, 0xbdd2d3e7, v153
	v_lshlrev_b32_e32 v154, 16, v77
	v_and_b32_e32 v155, 0xffff0000, v77
	v_mul_f32_e32 v111, v175, v111
	v_pk_add_f32 v[154:155], v[154:155], 0 op_sel_hi:[1,0]
	v_exp_f32_e32 v111, v111
	v_pk_add_f32 v[176:177], v[154:155], v[156:157]
	v_mul_f32_e32 v76, v174, v76
	v_pk_mul_f32 v[154:155], v[176:177], v[176:177]
	v_add_f32_e32 v102, 1.0, v111
	v_fmamk_f32 v77, v154, 0xbdd2d3e7, v153
	v_mul_f32_e32 v77, v176, v77
	v_exp_f32_e32 v111, v77
	v_fmamk_f32 v77, v155, 0xbdd2d3e7, v153
	v_mul_f32_e32 v77, v177, v77
	v_exp_f32_e32 v154, v77
	v_rcp_f32_e32 v77, v102
	v_add_f32_e32 v102, 1.0, v111
	v_rcp_f32_e32 v178, v102
	v_add_f32_e32 v102, 1.0, v154
	global_load_dwordx4 v[154:157], v[112:113], off offset:912
	global_load_dwordx4 v[160:163], v[112:113], off offset:896
	v_add_f32_e32 v74, 1.0, v74
	v_exp_f32_e32 v76, v76
	v_rcp_f32_e32 v74, v74
	v_pk_mul_f32 v[112:113], v[170:171], v[172:173]
	v_rcp_f32_e32 v179, v102
	v_add_f32_e32 v76, 1.0, v76
	v_rcp_f32_e32 v76, v76
	v_pk_mul_f32 v[74:75], v[168:169], v[74:75]
	v_pk_mul_f32 v[168:169], v[176:177], v[178:179]
	v_cvt_pk_bf16_f32 v74, v74, v75
	v_cvt_pk_bf16_f32 v75, v112, v113
	v_lshlrev_b32_e32 v112, 16, v70
	v_and_b32_e32 v113, 0xffff0000, v70
	v_pk_add_f32 v[112:113], v[112:113], 0 op_sel_hi:[1,0]
	v_pk_mul_f32 v[76:77], v[174:175], v[76:77]
	s_waitcnt vmcnt(2)
; #define LAS __attribute__((address_space(3)))
; DI bf16x8 pack8(f32x4 a, f32x4 b) { u32x4 p; p.x = pk2(a.x, a.y); p.y = pk2(a.z, a.w); p.z = pk2(b.x, b.y); p.w = pk2(b.z, b.w); return __builtin_bit_cast(bf16x8, p); }
; DI void w2_compute(const Args& a, LAS unsigned char* lds, int task, int lane, const u32x4 (&x0)[8], const u32x4 (&x1)[8]) {
;     ...
;     for (int ks = 0; ks < 8; ++ks) { const f32x4 c0 = *(const f32x4*)(cb + 32 * ks), c1 = *(const f32x4*)(cb + 32 * ks + 4);
;         f32x4 g0, g1;
;         g0.x = gelu_tanh(bf2f(x0[ks].x & 0xffffu) + bf2f(x1[ks].x & 0xffffu) + c0.x); g0.y = gelu_tanh(bf2f(x0[ks].x >> 16) + bf2f(x1[ks].x >> 16) + c0.y);
;         g0.z = gelu_tanh(bf2f(x0[ks].y & 0xffffu) + bf2f(x1[ks].y & 0xffffu) + c0.z); g0.w = gelu_tanh(bf2f(x0[ks].y >> 16) + bf2f(x1[ks].y >> 16) + c0.w);
;         g1.x = gelu_tanh(bf2f(x0[ks].z & 0xffffu) + bf2f(x1[ks].z & 0xffffu) + c1.x); g1.y = gelu_tanh(bf2f(x0[ks].z >> 16) + bf2f(x1[ks].z >> 16) + c1.y);
;         g1.z = gelu_tanh(bf2f(x0[ks].w & 0xffffu) + bf2f(x1[ks].w & 0xffffu) + c1.z); g1.w = gelu_tanh(bf2f(x0[ks].w >> 16) + bf2f(x1[ks].w >> 16) + c1.w);
;         af[ks] = pack8(g0, g1); }
;     const LAS unsigned char* wl = lds + W2_LDS + kind * 32768;
;     f32x4 acc[4];
; #pragma unroll
;     for (int nt = 0; nt < 4; ++nt) { acc[nt] = (f32x4){0.f, 0.f, 0.f, 0.f};
; #pragma unroll
;         for (int ks = 0; ks < 8; ++ks) { const bf16x8 wfr = *(const LAS bf16x8*)(wl + w2off(16 * (fr >> 2) + 4 * nt + (fr & 3), 4 * ks + fq)); acc[nt] = __builtin_amdgcn_mfma_f32_16x16x32_bf16(wfr, af[ks], acc[nt], 0, 0, 0); } }
	v_pk_add_f32 v[112:113], v[112:113], v[164:165]
	s_nop 0
	v_pk_mul_f32 v[164:165], v[112:113], v[112:113]
	v_cvt_pk_bf16_f32 v76, v76, v77
	v_fmamk_f32 v70, v164, 0xbdd2d3e7, v153
	v_fmamk_f32 v77, v165, 0xbdd2d3e7, v153
	v_lshlrev_b32_e32 v164, 16, v71
	v_and_b32_e32 v165, 0xffff0000, v71
	v_pk_add_f32 v[164:165], v[164:165], 0 op_sel_hi:[1,0]
	v_mul_f32_e32 v77, v113, v77
	v_pk_add_f32 v[164:165], v[164:165], v[166:167]
	v_exp_f32_e32 v102, v77
	v_pk_mul_f32 v[166:167], v[164:165], v[164:165]
	v_cvt_pk_bf16_f32 v77, v168, v169
	v_fmamk_f32 v71, v166, 0xbdd2d3e7, v153
	v_mul_f32_e32 v71, v164, v71
	v_exp_f32_e32 v111, v71
	v_lshlrev_b32_e32 v168, 16, v72
	v_and_b32_e32 v169, 0xffff0000, v72
	v_pk_add_f32 v[168:169], v[168:169], 0 op_sel_hi:[1,0]
	v_fmamk_f32 v71, v167, 0xbdd2d3e7, v153
	v_pk_add_f32 v[98:99], v[168:169], v[98:99]
	v_add_f32_e32 v102, 1.0, v102
	v_mul_f32_e32 v71, v165, v71
	v_pk_mul_f32 v[168:169], v[98:99], v[98:99]
	v_exp_f32_e32 v167, v71
	v_rcp_f32_e32 v71, v102
	v_add_f32_e32 v102, 1.0, v111
	v_fmamk_f32 v72, v168, 0xbdd2d3e7, v153
	v_fmamk_f32 v111, v169, 0xbdd2d3e7, v153
	v_lshlrev_b32_e32 v168, 16, v73
	v_and_b32_e32 v169, 0xffff0000, v73
	v_mul_f32_e32 v111, v99, v111
	v_pk_add_f32 v[168:169], v[168:169], 0 op_sel_hi:[1,0]
	v_exp_f32_e32 v111, v111
	v_pk_add_f32 v[100:101], v[168:169], v[100:101]
	v_rcp_f32_e32 v166, v102
	v_pk_mul_f32 v[168:169], v[100:101], v[100:101]
	v_add_f32_e32 v102, 1.0, v167
	v_fmamk_f32 v73, v168, 0xbdd2d3e7, v153
	v_mul_f32_e32 v73, v100, v73
	v_rcp_f32_e32 v167, v102
	v_add_f32_e32 v102, 1.0, v111
	v_exp_f32_e32 v111, v73
	v_fmamk_f32 v73, v169, 0xbdd2d3e7, v153
	v_mul_f32_e32 v72, v98, v72
	v_mul_f32_e32 v73, v101, v73
	v_exp_f32_e32 v72, v72
	v_exp_f32_e32 v169, v73
	v_mul_f32_e32 v70, v112, v70
	v_exp_f32_e32 v70, v70
	v_rcp_f32_e32 v73, v102
	v_add_f32_e32 v102, 1.0, v111
	v_add_f32_e32 v72, 1.0, v72
	v_rcp_f32_e32 v168, v102
	v_add_f32_e32 v102, 1.0, v169
	v_rcp_f32_e32 v72, v72
	v_rcp_f32_e32 v169, v102
	v_add_f32_e32 v70, 1.0, v70
	v_rcp_f32_e32 v70, v70
	v_pk_mul_f32 v[72:73], v[98:99], v[72:73]
	v_pk_mul_f32 v[98:99], v[100:101], v[168:169]
	v_lshlrev_b32_e32 v100, 16, v66
	v_and_b32_e32 v101, 0xffff0000, v66
	v_pk_add_f32 v[100:101], v[100:101], 0 op_sel_hi:[1,0]
	v_pk_mul_f32 v[70:71], v[112:113], v[70:71]
	v_pk_mul_f32 v[112:113], v[164:165], v[166:167]
	s_waitcnt vmcnt(0)
	v_pk_add_f32 v[100:101], v[100:101], v[160:161]
	v_cvt_pk_bf16_f32 v70, v70, v71
	v_cvt_pk_bf16_f32 v71, v112, v113
	v_pk_mul_f32 v[112:113], v[100:101], v[100:101]
	v_cvt_pk_bf16_f32 v72, v72, v73
	v_fmamk_f32 v66, v112, 0xbdd2d3e7, v153
	v_mul_f32_e32 v66, v100, v66
	v_fmamk_f32 v73, v113, 0xbdd2d3e7, v153
	v_exp_f32_e32 v66, v66
	v_mul_f32_e32 v73, v101, v73
	v_exp_f32_e32 v102, v73
	v_cvt_pk_bf16_f32 v73, v98, v99
	v_add_f32_e32 v66, 1.0, v66
	v_rcp_f32_e32 v98, v66
	v_add_f32_e32 v66, 1.0, v102
	v_rcp_f32_e32 v99, v66
	v_lshlrev_b32_e32 v66, 16, v67
	v_and_b32_e32 v67, 0xffff0000, v67
	v_pk_add_f32 v[66:67], v[66:67], 0 op_sel_hi:[1,0]
	v_pk_mul_f32 v[164:165], v[100:101], v[98:99]
	v_pk_add_f32 v[112:113], v[66:67], v[162:163]
	v_add_u32_e32 v102, s9, v114
	v_pk_mul_f32 v[66:67], v[112:113], v[112:113]
	v_add_u32_e32 v160, v102, v118
	v_fmamk_f32 v66, v66, 0xbdd2d3e7, v153
	v_mul_f32_e32 v66, v112, v66
	v_fmamk_f32 v67, v67, 0xbdd2d3e7, v153
	v_exp_f32_e32 v66, v66
	v_mul_f32_e32 v67, v113, v67
	v_exp_f32_e32 v67, v67
	ds_read_b128 v[160:163], v160
	v_add_f32_e32 v66, 1.0, v66
	v_rcp_f32_e32 v166, v66
	v_add_f32_e32 v98, 1.0, v67
	v_lshlrev_b32_e32 v66, 16, v68
	v_and_b32_e32 v67, 0xffff0000, v68
	v_pk_add_f32 v[66:67], v[66:67], 0 op_sel_hi:[1,0]
	v_rcp_f32_e32 v167, v98
	v_pk_add_f32 v[168:169], v[66:67], v[154:155]
	v_pk_mul_f32 v[112:113], v[112:113], v[166:167]
	v_pk_mul_f32 v[66:67], v[168:169], v[168:169]
	s_nop 0
	v_fmamk_f32 v66, v66, 0xbdd2d3e7, v153
	v_mul_f32_e32 v66, v168, v66
	v_fmamk_f32 v67, v67, 0xbdd2d3e7, v153
	v_exp_f32_e32 v66, v66
	v_mul_f32_e32 v67, v169, v67
	v_exp_f32_e32 v67, v67
	v_add_f32_e32 v66, 1.0, v66
	v_rcp_f32_e32 v170, v66
	v_add_f32_e32 v98, 1.0, v67
	v_lshlrev_b32_e32 v66, 16, v69
	v_and_b32_e32 v67, 0xffff0000, v69
	v_pk_add_f32 v[66:67], v[66:67], 0 op_sel_hi:[1,0]
	v_rcp_f32_e32 v171, v98
	v_pk_add_f32 v[172:173], v[66:67], v[156:157]
	v_add_u32_e32 v98, v102, v116
	v_pk_mul_f32 v[154:155], v[172:173], v[172:173]
	v_pk_mul_f32 v[166:167], v[168:169], v[170:171]
	v_fmamk_f32 v66, v154, 0xbdd2d3e7, v153
	v_mul_f32_e32 v66, v172, v66
	v_exp_f32_e32 v99, v66
	v_add_u32_e32 v66, v102, v115
	ds_read_b128 v[66:69], v66
	v_add_u32_e32 v154, v102, v117
	v_add_f32_e32 v111, 1.0, v99
	ds_read_b128 v[98:101], v98
	v_rcp_f32_e32 v174, v111
	v_fmamk_f32 v111, v155, 0xbdd2d3e7, v153
	ds_read_b128 v[154:157], v154
	s_waitcnt lgkmcnt(2)
	v_mfma_f32_16x16x32_bf16 v[66:69], v[66:69], v[90:93], 0
	v_mul_f32_e32 v111, v173, v111
	v_exp_f32_e32 v111, v111
	s_waitcnt lgkmcnt(1)
	v_mfma_f32_16x16x32_bf16 v[66:69], v[98:101], v[94:97], v[66:69]
	v_add_u32_e32 v98, v102, v119
	ds_read_b128 v[98:101], v98
	v_add_f32_e32 v111, 1.0, v111
	s_waitcnt lgkmcnt(1)
	v_mfma_f32_16x16x32_bf16 v[66:69], v[154:157], v[86:89], v[66:69]
	v_add_u32_e32 v154, v102, v120
	ds_read_b128 v[154:157], v154
	v_rcp_f32_e32 v175, v111
	v_mfma_f32_16x16x32_bf16 v[66:69], v[160:163], v[82:85], v[66:69]
	v_add_u32_e32 v111, v102, v121
	ds_read_b128 v[160:163], v111
	v_pk_mul_f32 v[168:169], v[172:173], v[174:175]
	s_waitcnt lgkmcnt(2)
	v_mfma_f32_16x16x32_bf16 v[66:69], v[98:101], v[78:81], v[66:69]
	v_add_u32_e32 v98, v102, v122
	ds_read_b128 v[98:101], v98
	v_add_u32_e32 v102, s9, v123
	s_waitcnt lgkmcnt(2)
; #define LAS __attribute__((address_space(3)))
; DI void st8bf_(bf16_t* p, f32x4 v0, f32x4 v1) { u32x4 w; w.x = pk2(v0.x, v0.y); w.y = pk2(v0.z, v0.w); w.z = pk2(v1.x, v1.y); w.w = pk2(v1.z, v1.w); *(u32x4*)p = w; }
; DI void w2_compute(const Args& a, LAS unsigned char* lds, int task, int lane, const u32x4 (&x0)[8], const u32x4 (&x1)[8]) {
;     ...
;     const LAS unsigned char* wl = lds + W2_LDS + kind * 32768;
;     f32x4 acc[4];
; #pragma unroll
;     for (int nt = 0; nt < 4; ++nt) { acc[nt] = (f32x4){0.f, 0.f, 0.f, 0.f};
; #pragma unroll
;         for (int ks = 0; ks < 8; ++ks) { const bf16x8 wfr = *(const LAS bf16x8*)(wl + w2off(16 * (fr >> 2) + 4 * nt + (fr & 3), 4 * ks + fq)); acc[nt] = __builtin_amdgcn_mfma_f32_16x16x32_bf16(wfr, af[ks], acc[nt], 0, 0, 0); } }
;     bf16_t* kc = (bf16_t*)(ws + WS_KC) + ((size_t)kind * AROWS + row0 + fr) * 64 + 16 * fq;
;     st8bf_(kc, acc[0], acc[1]); st8bf_(kc + 8, acc[2], acc[3]);
	v_mfma_f32_16x16x32_bf16 v[66:69], v[154:157], v[74:77], v[66:69]
	v_add_u32_e32 v111, v102, v124
	v_cvt_pk_bf16_f32 v154, v164, v165
	v_cvt_pk_bf16_f32 v155, v112, v113
	s_waitcnt lgkmcnt(1)
	v_mfma_f32_16x16x32_bf16 v[66:69], v[160:163], v[70:73], v[66:69]
	ds_read_b128 v[160:163], v111
	v_cvt_pk_bf16_f32 v156, v166, v167
	v_cvt_pk_bf16_f32 v157, v168, v169
	v_add_u32_e32 v111, v102, v126
	s_waitcnt lgkmcnt(0)
	v_mfma_f32_16x16x32_bf16 v[160:163], v[160:163], v[90:93], 0
	ds_read_b128 v[164:167], v111
	v_add_u32_e32 v111, v102, v127
	v_mfma_f32_16x16x32_bf16 v[66:69], v[98:101], v[154:157], v[66:69]
	v_add_u32_e32 v98, v102, v125
	ds_read_b128 v[98:101], v98
	s_waitcnt lgkmcnt(0)
	v_mfma_f32_16x16x32_bf16 v[98:101], v[98:101], v[94:97], v[160:163]
	s_nop 2
	ds_read_b128 v[160:163], v111
	v_add_u32_e32 v111, v102, v128
	v_cvt_pk_bf16_f32 v66, v66, v67
	v_mfma_f32_16x16x32_bf16 v[98:101], v[164:167], v[86:89], v[98:101]
	ds_read_b128 v[164:167], v111
	v_add_u32_e32 v111, v102, v129
	v_cvt_pk_bf16_f32 v67, v68, v69
	s_waitcnt lgkmcnt(1)
	v_mfma_f32_16x16x32_bf16 v[98:101], v[160:163], v[82:85], v[98:101]
	ds_read_b128 v[160:163], v111
	v_add_u32_e32 v111, v102, v130
	v_add_u32_e32 v102, v102, v131
	s_waitcnt lgkmcnt(1)
	v_mfma_f32_16x16x32_bf16 v[98:101], v[164:167], v[78:81], v[98:101]
	ds_read_b128 v[164:167], v111
	s_waitcnt lgkmcnt(1)
	v_mfma_f32_16x16x32_bf16 v[98:101], v[160:163], v[74:77], v[98:101]
	ds_read_b128 v[160:163], v102
	v_add_u32_e32 v102, s9, v132
	v_add_u32_e32 v111, v102, v133
	s_waitcnt lgkmcnt(1)
	v_mfma_f32_16x16x32_bf16 v[98:101], v[164:167], v[70:73], v[98:101]
	ds_read_b128 v[164:167], v111
	v_add_u32_e32 v111, v102, v134
	s_waitcnt lgkmcnt(1)
	v_mfma_f32_16x16x32_bf16 v[98:101], v[160:163], v[154:157], v[98:101]
	ds_read_b128 v[160:163], v111
	v_add_u32_e32 v111, v102, v135
	ds_read_b128 v[168:171], v111
	s_waitcnt lgkmcnt(2)
	v_mfma_f32_16x16x32_bf16 v[164:167], v[164:167], v[90:93], 0
	v_add_u32_e32 v111, v102, v136
	s_nop 1
	v_cvt_pk_bf16_f32 v68, v98, v99
	v_cvt_pk_bf16_f32 v69, v100, v101
	s_waitcnt lgkmcnt(1)
	v_mfma_f32_16x16x32_bf16 v[160:163], v[160:163], v[94:97], v[164:167]
	s_nop 2
	ds_read_b128 v[164:167], v111
	v_add_u32_e32 v111, v102, v137
	s_waitcnt lgkmcnt(1)
	v_mfma_f32_16x16x32_bf16 v[160:163], v[168:171], v[86:89], v[160:163]
	ds_read_b128 v[168:171], v111
	v_add_u32_e32 v111, v102, v138
	s_waitcnt lgkmcnt(1)
	v_mfma_f32_16x16x32_bf16 v[160:163], v[164:167], v[82:85], v[160:163]
	ds_read_b128 v[164:167], v111
	v_add_u32_e32 v111, v102, v139
	v_add_u32_e32 v102, v102, v140
	s_waitcnt lgkmcnt(1)
	v_mfma_f32_16x16x32_bf16 v[160:163], v[168:171], v[78:81], v[160:163]
	ds_read_b128 v[168:171], v111
	s_waitcnt lgkmcnt(1)
	v_mfma_f32_16x16x32_bf16 v[160:163], v[164:167], v[74:77], v[160:163]
	ds_read_b128 v[164:167], v102
	v_add_u32_e32 v102, s9, v141
	v_add_u32_e32 v111, v102, v142
	s_waitcnt lgkmcnt(1)
	v_mfma_f32_16x16x32_bf16 v[160:163], v[168:171], v[70:73], v[160:163]
	ds_read_b128 v[168:171], v111
	v_add_u32_e32 v111, v102, v143
	s_mul_hi_i32 s9, s10, 0x10800
	s_waitcnt lgkmcnt(1)
	v_mfma_f32_16x16x32_bf16 v[160:163], v[164:167], v[154:157], v[160:163]
	ds_read_b128 v[164:167], v111
	v_add_u32_e32 v111, v102, v144
	s_mul_i32 s10, s10, 0x10800
	s_waitcnt lgkmcnt(1)
	v_mfma_f32_16x16x32_bf16 v[90:93], v[168:171], v[90:93], 0
	ds_read_b128 v[168:171], v111
	s_add_u32 s10, s10, s37
	s_addc_u32 s9, s9, s12
	s_waitcnt lgkmcnt(1)
	v_mfma_f32_16x16x32_bf16 v[90:93], v[164:167], v[94:97], v[90:93]
	v_add_u32_e32 v94, v102, v145
	ds_read_b128 v[94:97], v94
	s_lshl_b32 s12, s8, 8
	s_waitcnt lgkmcnt(1)
	v_mfma_f32_16x16x32_bf16 v[86:89], v[168:171], v[86:89], v[90:93]
	s_ashr_i32 s13, s12, 31
	s_addk_i32 s11, 0x800
	s_nop 0
	v_add_u32_e32 v90, v102, v146
	ds_read_b128 v[90:93], v90
	s_waitcnt lgkmcnt(1)
	v_mfma_f32_16x16x32_bf16 v[82:85], v[94:97], v[82:85], v[86:89]
	s_nop 2
	v_add_u32_e32 v86, v102, v147
	ds_read_b128 v[86:89], v86
	s_waitcnt lgkmcnt(1)
	v_mfma_f32_16x16x32_bf16 v[78:81], v[90:93], v[78:81], v[82:85]
	s_nop 2
	v_add_u32_e32 v82, v102, v148
	ds_read_b128 v[82:85], v82
	s_waitcnt lgkmcnt(1)
	v_mfma_f32_16x16x32_bf16 v[74:77], v[86:89], v[74:77], v[78:81]
	v_and_b32_e32 v87, 0xffff0000, v64
	s_nop 1
	v_add_u32_e32 v78, v102, v149
	ds_read_b128 v[78:81], v78
	s_waitcnt lgkmcnt(1)
	v_mfma_f32_16x16x32_bf16 v[70:73], v[82:85], v[70:73], v[74:77]
	v_lshlrev_b32_e32 v82, 16, v62
	s_nop 1
	v_mov_b32_e32 v75, s9
	v_or_b32_e32 v74, s10, v1
	s_waitcnt lgkmcnt(0)
	v_mfma_f32_16x16x32_bf16 v[70:73], v[78:81], v[154:157], v[70:73]
	v_lshlrev_b64 v[74:75], 7, v[74:75]
	v_lshl_add_u64 v[74:75], v[108:109], 0, v[74:75]
	global_store_dwordx4 v[74:75], v[66:69], off
	v_lshlrev_b32_e32 v80, 16, v58
	v_and_b32_e32 v81, 0xffff0000, v58
	v_cvt_pk_bf16_f32 v66, v160, v161
	v_cvt_pk_bf16_f32 v67, v162, v163
	s_nop 0
	v_cvt_pk_bf16_f32 v68, v70, v71
	v_cvt_pk_bf16_f32 v69, v72, v73
	global_store_dwordx4 v[74:75], v[66:69], off offset:16
	v_and_b32_e32 v83, 0xffff0000, v62
	v_pk_add_f32 v[80:81], v[82:83], v[80:81]
	v_lshl_add_u64 v[66:67], s[12:13], 2, v[106:107]
	global_load_dwordx4 v[68:71], v[66:67], off
	global_load_dwordx4 v[72:75], v[66:67], off offset:16
	global_load_dwordx4 v[76:79], v[66:67], off offset:128
	v_lshlrev_b32_e32 v84, 16, v59
	v_and_b32_e32 v85, 0xffff0000, v59
	s_lshl_b32 s9, s8, 15
	s_add_i32 s9, s34, s9
	s_ashr_i32 s10, s11, 31
	s_waitcnt vmcnt(2)
; DI bf16x8 pack8(f32x4 a, f32x4 b) { u32x4 p; p.x = pk2(a.x, a.y); p.y = pk2(a.z, a.w); p.z = pk2(b.x, b.y); p.w = pk2(b.z, b.w); return __builtin_bit_cast(bf16x8, p); }
; DI void w2_compute(const Args& a, LAS unsigned char* lds, int task, int lane, const u32x4 (&x0)[8], const u32x4 (&x1)[8]) {
;     ...
;     for (int ks = 0; ks < 8; ++ks) { const f32x4 c0 = *(const f32x4*)(cb + 32 * ks), c1 = *(const f32x4*)(cb + 32 * ks + 4);
;         f32x4 g0, g1;
;         g0.x = gelu_tanh(bf2f(x0[ks].x & 0xffffu) + bf2f(x1[ks].x & 0xffffu) + c0.x); g0.y = gelu_tanh(bf2f(x0[ks].x >> 16) + bf2f(x1[ks].x >> 16) + c0.y);
;         g0.z = gelu_tanh(bf2f(x0[ks].y & 0xffffu) + bf2f(x1[ks].y & 0xffffu) + c0.z); g0.w = gelu_tanh(bf2f(x0[ks].y >> 16) + bf2f(x1[ks].y >> 16) + c0.w);
;         g1.x = gelu_tanh(bf2f(x0[ks].z & 0xffffu) + bf2f(x1[ks].z & 0xffffu) + c1.x); g1.y = gelu_tanh(bf2f(x0[ks].z >> 16) + bf2f(x1[ks].z >> 16) + c1.y);
;         g1.z = gelu_tanh(bf2f(x0[ks].w & 0xffffu) + bf2f(x1[ks].w & 0xffffu) + c1.z); g1.w = gelu_tanh(bf2f(x0[ks].w >> 16) + bf2f(x1[ks].w >> 16) + c1.w);
;         af[ks] = pack8(g0, g1); }
	v_pk_add_f32 v[68:69], v[80:81], v[68:69]
	s_nop 0
	v_pk_mul_f32 v[80:81], v[68:69], v[68:69]
	s_nop 0
	v_fmamk_f32 v58, v80, 0xbdd2d3e7, v153
	v_fmamk_f32 v62, v81, 0xbdd2d3e7, v153
	global_load_dwordx4 v[80:83], v[66:67], off offset:144
	v_mul_f32_e32 v62, v69, v62
	v_exp_f32_e32 v62, v62
	v_mul_f32_e32 v58, v68, v58
	v_exp_f32_e32 v58, v58
	v_add_f32_e32 v86, 1.0, v62
	v_lshlrev_b32_e32 v62, 16, v63
	v_and_b32_e32 v63, 0xffff0000, v63
	v_pk_add_f32 v[62:63], v[62:63], v[84:85]
	v_lshlrev_b32_e32 v84, 16, v60
	v_pk_add_f32 v[62:63], v[62:63], v[70:71]
	v_and_b32_e32 v85, 0xffff0000, v60
	v_pk_mul_f32 v[70:71], v[62:63], v[62:63]
	v_add_f32_e32 v58, 1.0, v58
	v_fmamk_f32 v59, v70, 0xbdd2d3e7, v153
	v_mul_f32_e32 v59, v62, v59
	v_exp_f32_e32 v70, v59
	v_fmamk_f32 v59, v71, 0xbdd2d3e7, v153
	v_mul_f32_e32 v59, v63, v59
	v_exp_f32_e32 v71, v59
	v_rcp_f32_e32 v59, v86
	v_lshlrev_b32_e32 v86, 16, v64
	v_pk_add_f32 v[84:85], v[86:87], v[84:85]
	v_add_f32_e32 v70, 1.0, v70
	s_waitcnt vmcnt(2)
	v_pk_add_f32 v[72:73], v[84:85], v[72:73]
	v_add_f32_e32 v71, 1.0, v71
	v_pk_mul_f32 v[84:85], v[72:73], v[72:73]
	v_rcp_f32_e32 v58, v58
	v_fmamk_f32 v64, v85, 0xbdd2d3e7, v153
	v_mul_f32_e32 v64, v73, v64
	v_exp_f32_e32 v64, v64
	v_fmamk_f32 v60, v84, 0xbdd2d3e7, v153
	v_lshlrev_b32_e32 v84, 16, v61
	v_and_b32_e32 v85, 0xffff0000, v61
	v_add_f32_e32 v86, 1.0, v64
	v_lshlrev_b32_e32 v64, 16, v65
	v_and_b32_e32 v65, 0xffff0000, v65
	v_pk_add_f32 v[64:65], v[64:65], v[84:85]
	v_mul_f32_e32 v60, v72, v60
	v_pk_add_f32 v[64:65], v[64:65], v[74:75]
	v_exp_f32_e32 v60, v60
	v_pk_mul_f32 v[74:75], v[64:65], v[64:65]
	v_rcp_f32_e32 v70, v70
	v_fmamk_f32 v61, v74, 0xbdd2d3e7, v153
	v_mul_f32_e32 v61, v64, v61
	v_exp_f32_e32 v74, v61
	v_fmamk_f32 v61, v75, 0xbdd2d3e7, v153
	v_mul_f32_e32 v61, v65, v61
	v_exp_f32_e32 v75, v61
	v_add_f32_e32 v60, 1.0, v60
	v_add_f32_e32 v74, 1.0, v74
	v_rcp_f32_e32 v60, v60
	v_add_f32_e32 v75, 1.0, v75
	v_rcp_f32_e32 v61, v86
	v_rcp_f32_e32 v74, v74
	v_rcp_f32_e32 v75, v75
	v_rcp_f32_e32 v71, v71
	v_pk_mul_f32 v[60:61], v[72:73], v[60:61]
	v_lshlrev_b32_e32 v84, 16, v54
	v_pk_mul_f32 v[72:73], v[64:65], v[74:75]
	v_lshlrev_b32_e32 v74, 16, v46
	v_and_b32_e32 v75, 0xffff0000, v46
	v_and_b32_e32 v85, 0xffff0000, v54
	v_pk_add_f32 v[74:75], v[84:85], v[74:75]
	v_pk_mul_f32 v[58:59], v[68:69], v[58:59]
	s_waitcnt vmcnt(1)
	v_pk_add_f32 v[74:75], v[74:75], v[76:77]
	v_pk_mul_f32 v[62:63], v[62:63], v[70:71]
	v_pk_mul_f32 v[76:77], v[74:75], v[74:75]
	v_cvt_pk_bf16_f32 v58, v58, v59
	v_fmamk_f32 v54, v77, 0xbdd2d3e7, v153
	v_cvt_pk_bf16_f32 v59, v62, v63
	global_load_dwordx4 v[62:65], v[66:67], off offset:272
	global_load_dwordx4 v[68:71], v[66:67], off offset:256
	v_mul_f32_e32 v54, v75, v54
	v_exp_f32_e32 v54, v54
	v_cvt_pk_bf16_f32 v60, v60, v61
	v_fmamk_f32 v46, v76, 0xbdd2d3e7, v153
	v_cvt_pk_bf16_f32 v61, v72, v73
	v_add_f32_e32 v76, 1.0, v54
	v_lshlrev_b32_e32 v72, 16, v47
	v_and_b32_e32 v73, 0xffff0000, v47
	v_lshlrev_b32_e32 v54, 16, v55
	v_and_b32_e32 v55, 0xffff0000, v55
	v_pk_add_f32 v[54:55], v[54:55], v[72:73]
	v_and_b32_e32 v77, 0xffff0000, v48
	v_pk_add_f32 v[54:55], v[54:55], v[78:79]
	v_lshlrev_b32_e32 v78, 16, v56
	v_pk_mul_f32 v[72:73], v[54:55], v[54:55]
	v_and_b32_e32 v79, 0xffff0000, v56
	v_fmamk_f32 v47, v72, 0xbdd2d3e7, v153
	v_mul_f32_e32 v47, v54, v47
	v_exp_f32_e32 v72, v47
	v_fmamk_f32 v47, v73, 0xbdd2d3e7, v153
	v_mul_f32_e32 v47, v55, v47
	v_exp_f32_e32 v73, v47
	v_rcp_f32_e32 v47, v76
	v_lshlrev_b32_e32 v76, 16, v48
	v_pk_add_f32 v[76:77], v[78:79], v[76:77]
	v_mul_f32_e32 v46, v74, v46
	s_waitcnt vmcnt(2)
	v_pk_add_f32 v[76:77], v[76:77], v[80:81]
	v_exp_f32_e32 v46, v46
	v_pk_mul_f32 v[78:79], v[76:77], v[76:77]
	v_add_f32_e32 v72, 1.0, v72
	v_fmamk_f32 v56, v79, 0xbdd2d3e7, v153
	v_mul_f32_e32 v56, v77, v56
	v_exp_f32_e32 v56, v56
	v_fmamk_f32 v48, v78, 0xbdd2d3e7, v153
	v_lshlrev_b32_e32 v78, 16, v49
	v_and_b32_e32 v79, 0xffff0000, v49
	v_add_f32_e32 v80, 1.0, v56
	v_lshlrev_b32_e32 v56, 16, v57
	v_and_b32_e32 v57, 0xffff0000, v57
	v_pk_add_f32 v[56:57], v[56:57], v[78:79]
	v_mul_f32_e32 v48, v76, v48
	v_pk_add_f32 v[56:57], v[56:57], v[82:83]
	v_exp_f32_e32 v48, v48
	v_pk_mul_f32 v[78:79], v[56:57], v[56:57]
	v_add_f32_e32 v46, 1.0, v46
	v_fmamk_f32 v49, v78, 0xbdd2d3e7, v153
	v_mul_f32_e32 v49, v56, v49
	v_exp_f32_e32 v78, v49
	v_fmamk_f32 v49, v79, 0xbdd2d3e7, v153
	v_mul_f32_e32 v49, v57, v49
	v_exp_f32_e32 v79, v49
	v_add_f32_e32 v73, 1.0, v73
	v_rcp_f32_e32 v46, v46
	v_rcp_f32_e32 v72, v72
	v_rcp_f32_e32 v73, v73
	v_add_f32_e32 v48, 1.0, v48
	v_add_f32_e32 v78, 1.0, v78
	v_add_f32_e32 v79, 1.0, v79
	v_rcp_f32_e32 v48, v48
	v_rcp_f32_e32 v49, v80
	v_rcp_f32_e32 v78, v78
	v_rcp_f32_e32 v79, v79
	v_pk_mul_f32 v[46:47], v[74:75], v[46:47]
	v_pk_mul_f32 v[54:55], v[54:55], v[72:73]
	v_pk_mul_f32 v[48:49], v[76:77], v[48:49]
	v_pk_mul_f32 v[76:77], v[56:57], v[78:79]
	v_cvt_pk_bf16_f32 v46, v46, v47
	v_cvt_pk_bf16_f32 v47, v54, v55
	global_load_dwordx4 v[54:57], v[66:67], off offset:400
	global_load_dwordx4 v[72:75], v[66:67], off offset:384
	v_lshlrev_b32_e32 v78, 16, v42
	v_and_b32_e32 v79, 0xffff0000, v42
	v_lshlrev_b32_e32 v80, 16, v50
	v_and_b32_e32 v81, 0xffff0000, v50
	v_pk_add_f32 v[78:79], v[80:81], v[78:79]
	v_cvt_pk_bf16_f32 v48, v48, v49
	s_waitcnt vmcnt(2)
; DI bf16x8 pack8(f32x4 a, f32x4 b) { u32x4 p; p.x = pk2(a.x, a.y); p.y = pk2(a.z, a.w); p.z = pk2(b.x, b.y); p.w = pk2(b.z, b.w); return __builtin_bit_cast(bf16x8, p); }
; DI void w2_compute(const Args& a, LAS unsigned char* lds, int task, int lane, const u32x4 (&x0)[8], const u32x4 (&x1)[8]) {
;     ...
;     for (int ks = 0; ks < 8; ++ks) { const f32x4 c0 = *(const f32x4*)(cb + 32 * ks), c1 = *(const f32x4*)(cb + 32 * ks + 4);
;         f32x4 g0, g1;
;         g0.x = gelu_tanh(bf2f(x0[ks].x & 0xffffu) + bf2f(x1[ks].x & 0xffffu) + c0.x); g0.y = gelu_tanh(bf2f(x0[ks].x >> 16) + bf2f(x1[ks].x >> 16) + c0.y);
;         g0.z = gelu_tanh(bf2f(x0[ks].y & 0xffffu) + bf2f(x1[ks].y & 0xffffu) + c0.z); g0.w = gelu_tanh(bf2f(x0[ks].y >> 16) + bf2f(x1[ks].y >> 16) + c0.w);
;         g1.x = gelu_tanh(bf2f(x0[ks].z & 0xffffu) + bf2f(x1[ks].z & 0xffffu) + c1.x); g1.y = gelu_tanh(bf2f(x0[ks].z >> 16) + bf2f(x1[ks].z >> 16) + c1.y);
;         g1.z = gelu_tanh(bf2f(x0[ks].w & 0xffffu) + bf2f(x1[ks].w & 0xffffu) + c1.z); g1.w = gelu_tanh(bf2f(x0[ks].w >> 16) + bf2f(x1[ks].w >> 16) + c1.w);
;         af[ks] = pack8(g0, g1); }
	v_pk_add_f32 v[68:69], v[78:79], v[68:69]
	s_nop 0
	v_pk_mul_f32 v[78:79], v[68:69], v[68:69]
	s_nop 0
	v_fmamk_f32 v49, v79, 0xbdd2d3e7, v153
	v_mul_f32_e32 v49, v69, v49
	v_exp_f32_e32 v50, v49
	v_fmamk_f32 v42, v78, 0xbdd2d3e7, v153
	v_cvt_pk_bf16_f32 v49, v76, v77
	v_lshlrev_b32_e32 v76, 16, v43
	v_add_f32_e32 v78, 1.0, v50
	v_and_b32_e32 v77, 0xffff0000, v43
	v_lshlrev_b32_e32 v50, 16, v51
	v_and_b32_e32 v51, 0xffff0000, v51
	v_pk_add_f32 v[50:51], v[50:51], v[76:77]
	v_lshlrev_b32_e32 v76, 16, v44
	v_pk_add_f32 v[50:51], v[50:51], v[70:71]
	v_and_b32_e32 v77, 0xffff0000, v44
	v_pk_mul_f32 v[70:71], v[50:51], v[50:51]
	v_and_b32_e32 v79, 0xffff0000, v52
	v_fmamk_f32 v43, v70, 0xbdd2d3e7, v153
	v_mul_f32_e32 v43, v50, v43
	v_exp_f32_e32 v70, v43
	v_fmamk_f32 v43, v71, 0xbdd2d3e7, v153
	v_mul_f32_e32 v43, v51, v43
	v_exp_f32_e32 v71, v43
	v_rcp_f32_e32 v43, v78
	v_lshlrev_b32_e32 v78, 16, v52
	v_pk_add_f32 v[76:77], v[78:79], v[76:77]
	v_mul_f32_e32 v42, v68, v42
	v_pk_add_f32 v[62:63], v[76:77], v[62:63]
	v_exp_f32_e32 v42, v42
	v_pk_mul_f32 v[76:77], v[62:63], v[62:63]
	v_add_f32_e32 v70, 1.0, v70
	v_fmamk_f32 v52, v77, 0xbdd2d3e7, v153
	v_mul_f32_e32 v52, v63, v52
	v_exp_f32_e32 v52, v52
	v_fmamk_f32 v44, v76, 0xbdd2d3e7, v153
	v_lshlrev_b32_e32 v76, 16, v45
	v_and_b32_e32 v77, 0xffff0000, v45
	v_add_f32_e32 v78, 1.0, v52
	v_lshlrev_b32_e32 v52, 16, v53
	v_and_b32_e32 v53, 0xffff0000, v53
	v_pk_add_f32 v[52:53], v[52:53], v[76:77]
	v_add_f32_e32 v71, 1.0, v71
	v_pk_add_f32 v[52:53], v[52:53], v[64:65]
	v_mul_f32_e32 v44, v62, v44
	v_pk_mul_f32 v[64:65], v[52:53], v[52:53]
	v_rcp_f32_e32 v70, v70
	v_fmamk_f32 v45, v64, 0xbdd2d3e7, v153
	v_mul_f32_e32 v45, v52, v45
	v_exp_f32_e32 v64, v45
	v_fmamk_f32 v45, v65, 0xbdd2d3e7, v153
	v_mul_f32_e32 v45, v53, v45
	v_exp_f32_e32 v44, v44
	v_rcp_f32_e32 v71, v71
	v_exp_f32_e32 v65, v45
	v_add_f32_e32 v42, 1.0, v42
	v_rcp_f32_e32 v42, v42
	v_add_f32_e32 v44, 1.0, v44
	v_add_f32_e32 v64, 1.0, v64
	v_add_f32_e32 v65, 1.0, v65
	v_pk_mul_f32 v[50:51], v[50:51], v[70:71]
	v_lshlrev_b32_e32 v70, 16, v30
	v_and_b32_e32 v71, 0xffff0000, v30
	v_lshlrev_b32_e32 v76, 16, v38
	v_and_b32_e32 v77, 0xffff0000, v38
	v_rcp_f32_e32 v44, v44
	v_rcp_f32_e32 v45, v78
	v_rcp_f32_e32 v64, v64
	v_rcp_f32_e32 v65, v65
	v_pk_add_f32 v[70:71], v[76:77], v[70:71]
	v_pk_mul_f32 v[42:43], v[68:69], v[42:43]
	s_waitcnt vmcnt(0)
	v_pk_add_f32 v[70:71], v[70:71], v[72:73]
	v_pk_mul_f32 v[44:45], v[62:63], v[44:45]
	v_pk_mul_f32 v[72:73], v[70:71], v[70:71]
	v_pk_mul_f32 v[68:69], v[52:53], v[64:65]
	v_fmamk_f32 v38, v73, 0xbdd2d3e7, v153
	v_cvt_pk_bf16_f32 v42, v42, v43
	v_cvt_pk_bf16_f32 v43, v50, v51
	global_load_dwordx4 v[50:53], v[66:67], off offset:528
	global_load_dwordx4 v[62:65], v[66:67], off offset:512
	v_mul_f32_e32 v38, v71, v38
	v_exp_f32_e32 v38, v38
	v_cvt_pk_bf16_f32 v44, v44, v45
	v_fmamk_f32 v30, v72, 0xbdd2d3e7, v153
	v_cvt_pk_bf16_f32 v45, v68, v69
	v_add_f32_e32 v72, 1.0, v38
	v_lshlrev_b32_e32 v68, 16, v31
	v_and_b32_e32 v69, 0xffff0000, v31
	v_lshlrev_b32_e32 v38, 16, v39
	v_and_b32_e32 v39, 0xffff0000, v39
	v_pk_add_f32 v[38:39], v[38:39], v[68:69]
	v_and_b32_e32 v73, 0xffff0000, v32
	v_pk_add_f32 v[38:39], v[38:39], v[74:75]
	v_lshlrev_b32_e32 v74, 16, v40
	v_pk_mul_f32 v[68:69], v[38:39], v[38:39]
	v_and_b32_e32 v75, 0xffff0000, v40
	v_fmamk_f32 v31, v68, 0xbdd2d3e7, v153
	v_mul_f32_e32 v31, v38, v31
	v_exp_f32_e32 v68, v31
	v_fmamk_f32 v31, v69, 0xbdd2d3e7, v153
	v_mul_f32_e32 v31, v39, v31
	v_exp_f32_e32 v69, v31
	v_rcp_f32_e32 v31, v72
	v_lshlrev_b32_e32 v72, 16, v32
	v_pk_add_f32 v[72:73], v[74:75], v[72:73]
	v_mul_f32_e32 v30, v70, v30
	v_pk_add_f32 v[54:55], v[72:73], v[54:55]
	v_exp_f32_e32 v30, v30
	v_pk_mul_f32 v[72:73], v[54:55], v[54:55]
	v_add_f32_e32 v68, 1.0, v68
	v_fmamk_f32 v40, v73, 0xbdd2d3e7, v153
	v_mul_f32_e32 v40, v55, v40
	v_exp_f32_e32 v40, v40
	v_fmamk_f32 v32, v72, 0xbdd2d3e7, v153
	v_lshlrev_b32_e32 v72, 16, v33
	v_and_b32_e32 v73, 0xffff0000, v33
	v_add_f32_e32 v74, 1.0, v40
	v_lshlrev_b32_e32 v40, 16, v41
	v_and_b32_e32 v41, 0xffff0000, v41
	v_pk_add_f32 v[40:41], v[40:41], v[72:73]
	v_mul_f32_e32 v32, v54, v32
	v_pk_add_f32 v[40:41], v[40:41], v[56:57]
	v_exp_f32_e32 v32, v32
	v_pk_mul_f32 v[56:57], v[40:41], v[40:41]
	v_add_f32_e32 v30, 1.0, v30
	v_fmamk_f32 v33, v56, 0xbdd2d3e7, v153
	v_mul_f32_e32 v33, v40, v33
	v_exp_f32_e32 v56, v33
	v_fmamk_f32 v33, v57, 0xbdd2d3e7, v153
	v_mul_f32_e32 v33, v41, v33
	v_exp_f32_e32 v57, v33
	v_add_f32_e32 v69, 1.0, v69
	v_rcp_f32_e32 v30, v30
	v_rcp_f32_e32 v68, v68
	v_rcp_f32_e32 v69, v69
	v_add_f32_e32 v32, 1.0, v32
	v_add_f32_e32 v56, 1.0, v56
	v_add_f32_e32 v57, 1.0, v57
	v_rcp_f32_e32 v32, v32
	v_rcp_f32_e32 v33, v74
	v_rcp_f32_e32 v56, v56
	v_rcp_f32_e32 v57, v57
	v_pk_mul_f32 v[30:31], v[70:71], v[30:31]
	v_pk_mul_f32 v[38:39], v[38:39], v[68:69]
	v_pk_mul_f32 v[32:33], v[54:55], v[32:33]
	v_pk_mul_f32 v[68:69], v[40:41], v[56:57]
	v_cvt_pk_bf16_f32 v30, v30, v31
	v_cvt_pk_bf16_f32 v31, v38, v39
	global_load_dwordx4 v[38:41], v[66:67], off offset:656
	global_load_dwordx4 v[54:57], v[66:67], off offset:640
	v_lshlrev_b32_e32 v70, 16, v26
	v_and_b32_e32 v71, 0xffff0000, v26
	v_lshlrev_b32_e32 v72, 16, v34
	v_and_b32_e32 v73, 0xffff0000, v34
	v_pk_add_f32 v[70:71], v[72:73], v[70:71]
	v_cvt_pk_bf16_f32 v32, v32, v33
	s_waitcnt vmcnt(2)
; DI bf16x8 pack8(f32x4 a, f32x4 b) { u32x4 p; p.x = pk2(a.x, a.y); p.y = pk2(a.z, a.w); p.z = pk2(b.x, b.y); p.w = pk2(b.z, b.w); return __builtin_bit_cast(bf16x8, p); }
; DI void w2_compute(const Args& a, LAS unsigned char* lds, int task, int lane, const u32x4 (&x0)[8], const u32x4 (&x1)[8]) {
;     ...
;     for (int ks = 0; ks < 8; ++ks) { const f32x4 c0 = *(const f32x4*)(cb + 32 * ks), c1 = *(const f32x4*)(cb + 32 * ks + 4);
;         f32x4 g0, g1;
;         g0.x = gelu_tanh(bf2f(x0[ks].x & 0xffffu) + bf2f(x1[ks].x & 0xffffu) + c0.x); g0.y = gelu_tanh(bf2f(x0[ks].x >> 16) + bf2f(x1[ks].x >> 16) + c0.y);
;         g0.z = gelu_tanh(bf2f(x0[ks].y & 0xffffu) + bf2f(x1[ks].y & 0xffffu) + c0.z); g0.w = gelu_tanh(bf2f(x0[ks].y >> 16) + bf2f(x1[ks].y >> 16) + c0.w);
;         g1.x = gelu_tanh(bf2f(x0[ks].z & 0xffffu) + bf2f(x1[ks].z & 0xffffu) + c1.x); g1.y = gelu_tanh(bf2f(x0[ks].z >> 16) + bf2f(x1[ks].z >> 16) + c1.y);
;         g1.z = gelu_tanh(bf2f(x0[ks].w & 0xffffu) + bf2f(x1[ks].w & 0xffffu) + c1.z); g1.w = gelu_tanh(bf2f(x0[ks].w >> 16) + bf2f(x1[ks].w >> 16) + c1.w);
;         af[ks] = pack8(g0, g1); }
	v_pk_add_f32 v[62:63], v[70:71], v[62:63]
	s_nop 0
	v_pk_mul_f32 v[70:71], v[62:63], v[62:63]
	s_nop 0
	v_fmamk_f32 v33, v71, 0xbdd2d3e7, v153
	v_mul_f32_e32 v33, v63, v33
	v_exp_f32_e32 v34, v33
	v_fmamk_f32 v26, v70, 0xbdd2d3e7, v153
	v_cvt_pk_bf16_f32 v33, v68, v69
	v_lshlrev_b32_e32 v68, 16, v27
	v_add_f32_e32 v70, 1.0, v34
	v_and_b32_e32 v69, 0xffff0000, v27
	v_lshlrev_b32_e32 v34, 16, v35
	v_and_b32_e32 v35, 0xffff0000, v35
	v_pk_add_f32 v[34:35], v[34:35], v[68:69]
	v_lshlrev_b32_e32 v68, 16, v28
	v_pk_add_f32 v[34:35], v[34:35], v[64:65]
	v_and_b32_e32 v69, 0xffff0000, v28
	v_pk_mul_f32 v[64:65], v[34:35], v[34:35]
	v_and_b32_e32 v71, 0xffff0000, v36
	v_fmamk_f32 v27, v64, 0xbdd2d3e7, v153
	v_mul_f32_e32 v27, v34, v27
	v_exp_f32_e32 v64, v27
	v_fmamk_f32 v27, v65, 0xbdd2d3e7, v153
	v_mul_f32_e32 v27, v35, v27
	v_exp_f32_e32 v65, v27
	v_rcp_f32_e32 v27, v70
	v_lshlrev_b32_e32 v70, 16, v36
	v_pk_add_f32 v[68:69], v[70:71], v[68:69]
	v_mul_f32_e32 v26, v62, v26
	v_pk_add_f32 v[50:51], v[68:69], v[50:51]
	v_exp_f32_e32 v26, v26
	v_pk_mul_f32 v[68:69], v[50:51], v[50:51]
	v_add_f32_e32 v64, 1.0, v64
	v_fmamk_f32 v36, v69, 0xbdd2d3e7, v153
	v_mul_f32_e32 v36, v51, v36
	v_exp_f32_e32 v36, v36
	v_fmamk_f32 v28, v68, 0xbdd2d3e7, v153
	v_lshlrev_b32_e32 v68, 16, v29
	v_and_b32_e32 v69, 0xffff0000, v29
	v_add_f32_e32 v70, 1.0, v36
	v_lshlrev_b32_e32 v36, 16, v37
	v_and_b32_e32 v37, 0xffff0000, v37
	v_pk_add_f32 v[36:37], v[36:37], v[68:69]
	v_add_f32_e32 v65, 1.0, v65
	v_pk_add_f32 v[36:37], v[36:37], v[52:53]
	v_mul_f32_e32 v28, v50, v28
	v_pk_mul_f32 v[52:53], v[36:37], v[36:37]
	v_rcp_f32_e32 v64, v64
	v_fmamk_f32 v29, v52, 0xbdd2d3e7, v153
	v_mul_f32_e32 v29, v36, v29
	v_exp_f32_e32 v52, v29
	v_fmamk_f32 v29, v53, 0xbdd2d3e7, v153
	v_mul_f32_e32 v29, v37, v29
	v_exp_f32_e32 v28, v28
	v_rcp_f32_e32 v65, v65
	v_exp_f32_e32 v53, v29
	v_add_f32_e32 v26, 1.0, v26
	v_rcp_f32_e32 v26, v26
	v_add_f32_e32 v28, 1.0, v28
	v_add_f32_e32 v52, 1.0, v52
	v_add_f32_e32 v53, 1.0, v53
	v_pk_mul_f32 v[34:35], v[34:35], v[64:65]
	v_lshlrev_b32_e32 v64, 16, v14
	v_and_b32_e32 v65, 0xffff0000, v14
	v_lshlrev_b32_e32 v68, 16, v22
	v_and_b32_e32 v69, 0xffff0000, v22
	v_rcp_f32_e32 v28, v28
	v_rcp_f32_e32 v29, v70
	v_rcp_f32_e32 v52, v52
	v_rcp_f32_e32 v53, v53
	v_pk_add_f32 v[64:65], v[68:69], v[64:65]
	v_pk_mul_f32 v[26:27], v[62:63], v[26:27]
	s_waitcnt vmcnt(0)
	v_pk_add_f32 v[54:55], v[64:65], v[54:55]
	v_pk_mul_f32 v[28:29], v[50:51], v[28:29]
	v_pk_mul_f32 v[64:65], v[54:55], v[54:55]
	v_pk_mul_f32 v[62:63], v[36:37], v[52:53]
	v_fmamk_f32 v22, v65, 0xbdd2d3e7, v153
	v_cvt_pk_bf16_f32 v26, v26, v27
	v_cvt_pk_bf16_f32 v27, v34, v35
	global_load_dwordx4 v[34:37], v[66:67], off offset:784
	global_load_dwordx4 v[50:53], v[66:67], off offset:768
	v_mul_f32_e32 v22, v55, v22
	v_exp_f32_e32 v22, v22
	v_cvt_pk_bf16_f32 v28, v28, v29
	v_fmamk_f32 v14, v64, 0xbdd2d3e7, v153
	v_cvt_pk_bf16_f32 v29, v62, v63
	v_add_f32_e32 v64, 1.0, v22
	v_lshlrev_b32_e32 v62, 16, v15
	v_and_b32_e32 v63, 0xffff0000, v15
	v_lshlrev_b32_e32 v22, 16, v23
	v_and_b32_e32 v23, 0xffff0000, v23
	v_pk_add_f32 v[22:23], v[22:23], v[62:63]
	v_lshlrev_b32_e32 v62, 16, v16
	v_pk_add_f32 v[22:23], v[22:23], v[56:57]
	v_and_b32_e32 v63, 0xffff0000, v16
	v_pk_mul_f32 v[56:57], v[22:23], v[22:23]
	v_and_b32_e32 v65, 0xffff0000, v24
	v_fmamk_f32 v15, v56, 0xbdd2d3e7, v153
	v_mul_f32_e32 v15, v22, v15
	v_exp_f32_e32 v56, v15
	v_fmamk_f32 v15, v57, 0xbdd2d3e7, v153
	v_mul_f32_e32 v15, v23, v15
	v_exp_f32_e32 v57, v15
	v_rcp_f32_e32 v15, v64
	v_lshlrev_b32_e32 v64, 16, v24
	v_pk_add_f32 v[62:63], v[64:65], v[62:63]
	v_mul_f32_e32 v14, v54, v14
	v_pk_add_f32 v[38:39], v[62:63], v[38:39]
	v_exp_f32_e32 v14, v14
	v_pk_mul_f32 v[62:63], v[38:39], v[38:39]
	v_add_f32_e32 v56, 1.0, v56
	v_fmamk_f32 v24, v63, 0xbdd2d3e7, v153
	v_mul_f32_e32 v24, v39, v24
	v_exp_f32_e32 v24, v24
	v_fmamk_f32 v16, v62, 0xbdd2d3e7, v153
	v_lshlrev_b32_e32 v62, 16, v17
	v_and_b32_e32 v63, 0xffff0000, v17
	v_add_f32_e32 v64, 1.0, v24
	v_lshlrev_b32_e32 v24, 16, v25
	v_and_b32_e32 v25, 0xffff0000, v25
	v_pk_add_f32 v[24:25], v[24:25], v[62:63]
	v_mul_f32_e32 v16, v38, v16
	v_pk_add_f32 v[24:25], v[24:25], v[40:41]
	v_exp_f32_e32 v16, v16
	v_pk_mul_f32 v[40:41], v[24:25], v[24:25]
	v_add_f32_e32 v14, 1.0, v14
	v_fmamk_f32 v17, v40, 0xbdd2d3e7, v153
	v_mul_f32_e32 v17, v24, v17
	v_exp_f32_e32 v40, v17
	v_fmamk_f32 v17, v41, 0xbdd2d3e7, v153
	v_mul_f32_e32 v17, v25, v17
	v_exp_f32_e32 v41, v17
	v_add_f32_e32 v57, 1.0, v57
	v_rcp_f32_e32 v14, v14
	v_rcp_f32_e32 v56, v56
	v_rcp_f32_e32 v57, v57
	v_add_f32_e32 v16, 1.0, v16
	v_add_f32_e32 v40, 1.0, v40
	v_add_f32_e32 v41, 1.0, v41
	v_rcp_f32_e32 v16, v16
	v_rcp_f32_e32 v17, v64
	v_rcp_f32_e32 v40, v40
	v_rcp_f32_e32 v41, v41
	v_pk_mul_f32 v[14:15], v[54:55], v[14:15]
	v_pk_mul_f32 v[22:23], v[22:23], v[56:57]
	v_pk_mul_f32 v[16:17], v[38:39], v[16:17]
	v_pk_mul_f32 v[54:55], v[24:25], v[40:41]
	v_cvt_pk_bf16_f32 v14, v14, v15
	v_cvt_pk_bf16_f32 v15, v22, v23
	global_load_dwordx4 v[22:25], v[66:67], off offset:912
	global_load_dwordx4 v[38:41], v[66:67], off offset:896
	v_lshlrev_b32_e32 v56, 16, v10
	v_and_b32_e32 v57, 0xffff0000, v10
	v_lshlrev_b32_e32 v62, 16, v18
	v_and_b32_e32 v63, 0xffff0000, v18
	v_pk_add_f32 v[56:57], v[62:63], v[56:57]
	v_cvt_pk_bf16_f32 v16, v16, v17
	s_waitcnt vmcnt(2)
; #define LAS __attribute__((address_space(3)))
; DI bf16x8 pack8(f32x4 a, f32x4 b) { u32x4 p; p.x = pk2(a.x, a.y); p.y = pk2(a.z, a.w); p.z = pk2(b.x, b.y); p.w = pk2(b.z, b.w); return __builtin_bit_cast(bf16x8, p); }
; DI void w2_compute(const Args& a, LAS unsigned char* lds, int task, int lane, const u32x4 (&x0)[8], const u32x4 (&x1)[8]) {
;     ...
;     for (int ks = 0; ks < 8; ++ks) { const f32x4 c0 = *(const f32x4*)(cb + 32 * ks), c1 = *(const f32x4*)(cb + 32 * ks + 4);
;         f32x4 g0, g1;
;         g0.x = gelu_tanh(bf2f(x0[ks].x & 0xffffu) + bf2f(x1[ks].x & 0xffffu) + c0.x); g0.y = gelu_tanh(bf2f(x0[ks].x >> 16) + bf2f(x1[ks].x >> 16) + c0.y);
;         g0.z = gelu_tanh(bf2f(x0[ks].y & 0xffffu) + bf2f(x1[ks].y & 0xffffu) + c0.z); g0.w = gelu_tanh(bf2f(x0[ks].y >> 16) + bf2f(x1[ks].y >> 16) + c0.w);
;         g1.x = gelu_tanh(bf2f(x0[ks].z & 0xffffu) + bf2f(x1[ks].z & 0xffffu) + c1.x); g1.y = gelu_tanh(bf2f(x0[ks].z >> 16) + bf2f(x1[ks].z >> 16) + c1.y);
;         g1.z = gelu_tanh(bf2f(x0[ks].w & 0xffffu) + bf2f(x1[ks].w & 0xffffu) + c1.z); g1.w = gelu_tanh(bf2f(x0[ks].w >> 16) + bf2f(x1[ks].w >> 16) + c1.w);
;         af[ks] = pack8(g0, g1); }
;     const LAS unsigned char* wl = lds + W2_LDS + kind * 32768;
;     f32x4 acc[4];
; #pragma unroll
;     for (int nt = 0; nt < 4; ++nt) { acc[nt] = (f32x4){0.f, 0.f, 0.f, 0.f};
; #pragma unroll
;         for (int ks = 0; ks < 8; ++ks) { const bf16x8 wfr = *(const LAS bf16x8*)(wl + w2off(16 * (fr >> 2) + 4 * nt + (fr & 3), 4 * ks + fq)); acc[nt] = __builtin_amdgcn_mfma_f32_16x16x32_bf16(wfr, af[ks], acc[nt], 0, 0, 0); } }
	v_pk_add_f32 v[50:51], v[56:57], v[50:51]
	s_nop 0
	v_pk_mul_f32 v[56:57], v[50:51], v[50:51]
	s_nop 0
	v_fmamk_f32 v17, v57, 0xbdd2d3e7, v153
	v_mul_f32_e32 v17, v51, v17
	v_exp_f32_e32 v18, v17
	v_fmamk_f32 v10, v56, 0xbdd2d3e7, v153
	v_cvt_pk_bf16_f32 v17, v54, v55
	v_lshlrev_b32_e32 v54, 16, v11
	v_add_f32_e32 v56, 1.0, v18
	v_and_b32_e32 v55, 0xffff0000, v11
	v_lshlrev_b32_e32 v18, 16, v19
	v_and_b32_e32 v19, 0xffff0000, v19
	v_pk_add_f32 v[18:19], v[18:19], v[54:55]
	v_lshlrev_b32_e32 v54, 16, v12
	v_pk_add_f32 v[18:19], v[18:19], v[52:53]
	v_and_b32_e32 v55, 0xffff0000, v12
	v_pk_mul_f32 v[52:53], v[18:19], v[18:19]
	v_and_b32_e32 v57, 0xffff0000, v20
	v_fmamk_f32 v11, v52, 0xbdd2d3e7, v153
	v_mul_f32_e32 v11, v18, v11
	v_exp_f32_e32 v52, v11
	v_fmamk_f32 v11, v53, 0xbdd2d3e7, v153
	v_mul_f32_e32 v11, v19, v11
	v_exp_f32_e32 v53, v11
	v_rcp_f32_e32 v11, v56
	v_lshlrev_b32_e32 v56, 16, v20
	v_pk_add_f32 v[54:55], v[56:57], v[54:55]
	v_mul_f32_e32 v10, v50, v10
	v_pk_add_f32 v[34:35], v[54:55], v[34:35]
	v_exp_f32_e32 v10, v10
	v_pk_mul_f32 v[54:55], v[34:35], v[34:35]
	v_add_f32_e32 v52, 1.0, v52
	v_fmamk_f32 v20, v55, 0xbdd2d3e7, v153
	v_mul_f32_e32 v20, v35, v20
	v_exp_f32_e32 v20, v20
	v_fmamk_f32 v12, v54, 0xbdd2d3e7, v153
	v_lshlrev_b32_e32 v54, 16, v13
	v_and_b32_e32 v55, 0xffff0000, v13
	v_add_f32_e32 v56, 1.0, v20
	v_lshlrev_b32_e32 v20, 16, v21
	v_and_b32_e32 v21, 0xffff0000, v21
	v_pk_add_f32 v[20:21], v[20:21], v[54:55]
	v_mul_f32_e32 v12, v34, v12
	v_pk_add_f32 v[20:21], v[20:21], v[36:37]
	v_exp_f32_e32 v12, v12
	v_pk_mul_f32 v[36:37], v[20:21], v[20:21]
	v_add_f32_e32 v10, 1.0, v10
	v_fmamk_f32 v13, v36, 0xbdd2d3e7, v153
	v_mul_f32_e32 v13, v20, v13
	v_add_f32_e32 v53, 1.0, v53
	v_exp_f32_e32 v36, v13
	v_fmamk_f32 v13, v37, 0xbdd2d3e7, v153
	v_rcp_f32_e32 v10, v10
	v_rcp_f32_e32 v52, v52
	v_rcp_f32_e32 v53, v53
	v_add_f32_e32 v12, 1.0, v12
	v_mul_f32_e32 v13, v21, v13
	v_rcp_f32_e32 v12, v12
	v_exp_f32_e32 v37, v13
	v_rcp_f32_e32 v13, v56
	v_pk_mul_f32 v[10:11], v[50:51], v[10:11]
	v_pk_mul_f32 v[18:19], v[18:19], v[52:53]
	v_cvt_pk_bf16_f32 v10, v10, v11
	v_pk_mul_f32 v[12:13], v[34:35], v[12:13]
	v_cvt_pk_bf16_f32 v11, v18, v19
	v_lshlrev_b32_e32 v18, 16, v2
	v_and_b32_e32 v19, 0xffff0000, v2
	v_lshlrev_b32_e32 v34, 16, v6
	v_and_b32_e32 v35, 0xffff0000, v6
	v_pk_add_f32 v[18:19], v[18:19], v[34:35]
	v_add_f32_e32 v36, 1.0, v36
	s_waitcnt vmcnt(0)
	v_pk_add_f32 v[18:19], v[18:19], v[38:39]
	v_add_f32_e32 v37, 1.0, v37
	v_pk_mul_f32 v[34:35], v[18:19], v[18:19]
	v_rcp_f32_e32 v36, v36
	v_fmamk_f32 v2, v34, 0xbdd2d3e7, v153
	v_mul_f32_e32 v2, v18, v2
	v_fmamk_f32 v6, v35, 0xbdd2d3e7, v153
	v_rcp_f32_e32 v37, v37
	v_exp_f32_e32 v2, v2
	v_mul_f32_e32 v6, v19, v6
	v_exp_f32_e32 v6, v6
	v_pk_mul_f32 v[20:21], v[20:21], v[36:37]
	v_add_f32_e32 v2, 1.0, v2
	v_cvt_pk_bf16_f32 v12, v12, v13
	v_cvt_pk_bf16_f32 v13, v20, v21
	v_rcp_f32_e32 v20, v2
	v_add_f32_e32 v2, 1.0, v6
	v_rcp_f32_e32 v21, v2
	v_lshlrev_b32_e32 v2, 16, v3
	v_and_b32_e32 v3, 0xffff0000, v3
	v_lshlrev_b32_e32 v6, 16, v7
	v_and_b32_e32 v7, 0xffff0000, v7
	v_pk_add_f32 v[2:3], v[2:3], v[6:7]
	v_pk_mul_f32 v[36:37], v[18:19], v[20:21]
	v_pk_add_f32 v[34:35], v[2:3], v[40:41]
	v_lshlrev_b32_e32 v6, 16, v8
	v_pk_mul_f32 v[2:3], v[34:35], v[34:35]
	v_and_b32_e32 v7, 0xffff0000, v8
	v_fmamk_f32 v2, v2, 0xbdd2d3e7, v153
	v_mul_f32_e32 v2, v34, v2
	v_fmamk_f32 v3, v3, 0xbdd2d3e7, v153
	v_exp_f32_e32 v2, v2
	v_mul_f32_e32 v3, v35, v3
	v_exp_f32_e32 v3, v3
	v_add_u32_e32 v56, s9, v114
	v_add_f32_e32 v2, 1.0, v2
	v_rcp_f32_e32 v38, v2
	v_add_f32_e32 v18, 1.0, v3
	v_lshlrev_b32_e32 v2, 16, v4
	v_and_b32_e32 v3, 0xffff0000, v4
	v_pk_add_f32 v[2:3], v[2:3], v[6:7]
	v_lshlrev_b32_e32 v4, 16, v9
	v_pk_add_f32 v[40:41], v[2:3], v[22:23]
	v_rcp_f32_e32 v39, v18
	v_pk_mul_f32 v[2:3], v[40:41], v[40:41]
	v_pk_mul_f32 v[34:35], v[34:35], v[38:39]
	v_fmamk_f32 v2, v2, 0xbdd2d3e7, v153
	v_mul_f32_e32 v2, v40, v2
	v_fmamk_f32 v3, v3, 0xbdd2d3e7, v153
	v_exp_f32_e32 v2, v2
	v_mul_f32_e32 v3, v41, v3
	v_exp_f32_e32 v3, v3
	v_add_f32_e32 v2, 1.0, v2
	v_rcp_f32_e32 v50, v2
	v_add_f32_e32 v6, 1.0, v3
	v_lshlrev_b32_e32 v2, 16, v5
	v_and_b32_e32 v3, 0xffff0000, v5
	v_and_b32_e32 v5, 0xffff0000, v9
	v_pk_add_f32 v[2:3], v[2:3], v[4:5]
	v_rcp_f32_e32 v51, v6
	v_pk_add_f32 v[52:53], v[2:3], v[24:25]
	v_add_u32_e32 v6, v56, v116
	v_pk_mul_f32 v[18:19], v[52:53], v[52:53]
	v_pk_mul_f32 v[38:39], v[40:41], v[50:51]
	v_fmamk_f32 v2, v18, 0xbdd2d3e7, v153
	v_mul_f32_e32 v2, v52, v2
	v_exp_f32_e32 v7, v2
	v_add_u32_e32 v2, v56, v115
	ds_read_b128 v[2:5], v2
	v_fmamk_f32 v22, v19, 0xbdd2d3e7, v153
	v_add_f32_e32 v18, 1.0, v7
	ds_read_b128 v[6:9], v6
	v_rcp_f32_e32 v54, v18
	v_add_u32_e32 v18, v56, v117
	ds_read_b128 v[18:21], v18
	s_waitcnt lgkmcnt(2)
	v_mfma_f32_16x16x32_bf16 v[2:5], v[2:5], v[58:61], 0
	v_mul_f32_e32 v55, v53, v22
	v_add_u32_e32 v22, v56, v118
	ds_read_b128 v[22:25], v22
	s_waitcnt lgkmcnt(2)
	v_mfma_f32_16x16x32_bf16 v[2:5], v[6:9], v[46:49], v[2:5]
	v_add_u32_e32 v6, v56, v119
	ds_read_b128 v[6:9], v6
	v_exp_f32_e32 v55, v55
	s_waitcnt lgkmcnt(2)
	v_mfma_f32_16x16x32_bf16 v[2:5], v[18:21], v[42:45], v[2:5]
	v_add_u32_e32 v18, v56, v120
	ds_read_b128 v[18:21], v18
	v_add_f32_e32 v55, 1.0, v55
	s_waitcnt lgkmcnt(2)
; #define LAS __attribute__((address_space(3)))
; DI void st8bf_(bf16_t* p, f32x4 v0, f32x4 v1) { u32x4 w; w.x = pk2(v0.x, v0.y); w.y = pk2(v0.z, v0.w); w.z = pk2(v1.x, v1.y); w.w = pk2(v1.z, v1.w); *(u32x4*)p = w; }
; DI void w2_compute(const Args& a, LAS unsigned char* lds, int task, int lane, const u32x4 (&x0)[8], const u32x4 (&x1)[8]) {
;     ...
;     const LAS unsigned char* wl = lds + W2_LDS + kind * 32768;
;     f32x4 acc[4];
; #pragma unroll
;     for (int nt = 0; nt < 4; ++nt) { acc[nt] = (f32x4){0.f, 0.f, 0.f, 0.f};
; #pragma unroll
;         for (int ks = 0; ks < 8; ++ks) { const bf16x8 wfr = *(const LAS bf16x8*)(wl + w2off(16 * (fr >> 2) + 4 * nt + (fr & 3), 4 * ks + fq)); acc[nt] = __builtin_amdgcn_mfma_f32_16x16x32_bf16(wfr, af[ks], acc[nt], 0, 0, 0); } }
;     bf16_t* kc = (bf16_t*)(ws + WS_KC) + ((size_t)kind * AROWS + row0 + fr) * 64 + 16 * fq;
;     st8bf_(kc, acc[0], acc[1]); st8bf_(kc + 8, acc[2], acc[3]);
	v_mfma_f32_16x16x32_bf16 v[2:5], v[22:25], v[30:33], v[2:5]
	v_add_u32_e32 v22, v56, v121
	ds_read_b128 v[22:25], v22
	v_rcp_f32_e32 v55, v55
	s_waitcnt lgkmcnt(2)
	v_mfma_f32_16x16x32_bf16 v[2:5], v[6:9], v[26:29], v[2:5]
	v_add_u32_e32 v6, v56, v122
	ds_read_b128 v[6:9], v6
	v_add_u32_e32 v50, s9, v123
	s_waitcnt lgkmcnt(2)
	v_mfma_f32_16x16x32_bf16 v[2:5], v[18:21], v[14:17], v[2:5]
	v_add_u32_e32 v19, v50, v124
	v_pk_mul_f32 v[40:41], v[52:53], v[54:55]
	v_cvt_pk_bf16_f32 v18, v36, v37
	s_waitcnt lgkmcnt(1)
	v_mfma_f32_16x16x32_bf16 v[2:5], v[22:25], v[10:13], v[2:5]
	ds_read_b128 v[22:25], v19
	v_cvt_pk_bf16_f32 v19, v34, v35
	v_cvt_pk_bf16_f32 v20, v38, v39
	v_cvt_pk_bf16_f32 v21, v40, v41
	s_waitcnt lgkmcnt(0)
	v_mfma_f32_16x16x32_bf16 v[22:25], v[22:25], v[58:61], 0
	v_add_u32_e32 v34, v50, v126
	ds_read_b128 v[34:37], v34
	v_add_u32_e32 v54, s9, v141
	v_mfma_f32_16x16x32_bf16 v[2:5], v[6:9], v[18:21], v[2:5]
	v_add_u32_e32 v6, v50, v125
	ds_read_b128 v[6:9], v6
	s_waitcnt lgkmcnt(0)
	v_mfma_f32_16x16x32_bf16 v[6:9], v[6:9], v[46:49], v[22:25]
	s_nop 2
	v_add_u32_e32 v22, v50, v127
	ds_read_b128 v[22:25], v22
	v_cvt_pk_bf16_f32 v2, v2, v3
	v_mfma_f32_16x16x32_bf16 v[6:9], v[34:37], v[42:45], v[6:9]
	v_add_u32_e32 v34, v50, v128
	ds_read_b128 v[34:37], v34
	v_cvt_pk_bf16_f32 v3, v4, v5
	s_waitcnt lgkmcnt(1)
	v_mfma_f32_16x16x32_bf16 v[6:9], v[22:25], v[30:33], v[6:9]
	v_add_u32_e32 v22, v50, v129
	ds_read_b128 v[22:25], v22
	s_waitcnt lgkmcnt(1)
	v_mfma_f32_16x16x32_bf16 v[6:9], v[34:37], v[26:29], v[6:9]
	v_add_u32_e32 v34, v50, v130
	ds_read_b128 v[34:37], v34
	s_waitcnt lgkmcnt(1)
	v_mfma_f32_16x16x32_bf16 v[6:9], v[22:25], v[14:17], v[6:9]
	v_add_u32_e32 v22, v50, v131
	ds_read_b128 v[22:25], v22
	v_add_u32_e32 v50, s9, v132
	s_waitcnt lgkmcnt(1)
	v_mfma_f32_16x16x32_bf16 v[6:9], v[34:37], v[10:13], v[6:9]
	v_add_u32_e32 v34, v50, v133
	ds_read_b128 v[34:37], v34
	v_add_u32_e32 v38, v50, v135
	s_waitcnt lgkmcnt(1)
	v_mfma_f32_16x16x32_bf16 v[6:9], v[22:25], v[18:21], v[6:9]
	v_add_u32_e32 v22, v50, v134
	ds_read_b128 v[22:25], v22
	ds_read_b128 v[38:41], v38
	s_waitcnt lgkmcnt(2)
	v_mfma_f32_16x16x32_bf16 v[34:37], v[34:37], v[58:61], 0
	s_mul_hi_i32 s9, s8, 0x10800
	s_mul_i32 s8, s8, 0x10800
	s_add_u32 s8, s8, s11
	s_waitcnt lgkmcnt(1)
	v_mfma_f32_16x16x32_bf16 v[22:25], v[22:25], v[46:49], v[34:37]
	s_addc_u32 s9, s9, s10
	s_nop 1
	v_add_u32_e32 v34, v50, v136
	ds_read_b128 v[34:37], v34
	s_waitcnt lgkmcnt(1)
	v_mfma_f32_16x16x32_bf16 v[22:25], v[38:41], v[42:45], v[22:25]
	v_add_u32_e32 v38, v50, v137
	ds_read_b128 v[38:41], v38
	v_cvt_pk_bf16_f32 v4, v6, v7
	s_waitcnt lgkmcnt(1)
	v_mfma_f32_16x16x32_bf16 v[22:25], v[34:37], v[30:33], v[22:25]
	v_add_u32_e32 v34, v50, v138
	ds_read_b128 v[34:37], v34
	v_cvt_pk_bf16_f32 v5, v8, v9
	s_waitcnt lgkmcnt(1)
	v_mfma_f32_16x16x32_bf16 v[22:25], v[38:41], v[26:29], v[22:25]
	v_add_u32_e32 v38, v50, v139
	ds_read_b128 v[38:41], v38
	s_waitcnt lgkmcnt(1)
	v_mfma_f32_16x16x32_bf16 v[22:25], v[34:37], v[14:17], v[22:25]
	v_add_u32_e32 v34, v50, v140
	ds_read_b128 v[34:37], v34
	v_add_u32_e32 v50, v54, v144
	s_waitcnt lgkmcnt(1)
	v_mfma_f32_16x16x32_bf16 v[22:25], v[38:41], v[10:13], v[22:25]
	v_add_u32_e32 v38, v54, v142
	ds_read_b128 v[38:41], v38
	ds_read_b128 v[50:53], v50
	s_waitcnt lgkmcnt(2)
	v_mfma_f32_16x16x32_bf16 v[22:25], v[34:37], v[18:21], v[22:25]
	v_add_u32_e32 v34, v54, v143
	ds_read_b128 v[34:37], v34
	s_waitcnt lgkmcnt(2)
	v_mfma_f32_16x16x32_bf16 v[38:41], v[38:41], v[58:61], 0
	s_waitcnt lgkmcnt(0)
	v_mfma_f32_16x16x32_bf16 v[34:37], v[34:37], v[46:49], v[38:41]
	s_nop 5
	v_add_u32_e32 v38, v54, v145
	ds_read_b128 v[38:41], v38
	v_mfma_f32_16x16x32_bf16 v[34:37], v[50:53], v[42:45], v[34:37]
	v_add_u32_e32 v42, v54, v146
	ds_read_b128 v[42:45], v42
	s_waitcnt lgkmcnt(1)
	v_mfma_f32_16x16x32_bf16 v[30:33], v[38:41], v[30:33], v[34:37]
	s_nop 3
	v_add_u32_e32 v34, v54, v147
	ds_read_b128 v[34:37], v34
	s_waitcnt lgkmcnt(1)
	v_mfma_f32_16x16x32_bf16 v[26:29], v[42:45], v[26:29], v[30:33]
	s_nop 2
	v_add_u32_e32 v30, v54, v148
	ds_read_b128 v[30:33], v30
	s_waitcnt lgkmcnt(1)
	v_mfma_f32_16x16x32_bf16 v[14:17], v[34:37], v[14:17], v[26:29]
	s_nop 2
	v_add_u32_e32 v26, v54, v149
	ds_read_b128 v[26:29], v26
	s_waitcnt lgkmcnt(1)
	v_mfma_f32_16x16x32_bf16 v[10:13], v[30:33], v[10:13], v[14:17]
	s_nop 2
	v_mov_b32_e32 v15, s9
	v_or_b32_e32 v14, s8, v1
	s_waitcnt lgkmcnt(0)
	v_mfma_f32_16x16x32_bf16 v[10:13], v[26:29], v[18:21], v[10:13]
	v_lshlrev_b64 v[14:15], 7, v[14:15]
	v_lshl_add_u64 v[14:15], v[108:109], 0, v[14:15]
	global_store_dwordx4 v[14:15], v[2:5], off
	s_nop 1
	v_cvt_pk_bf16_f32 v2, v22, v23
	v_cvt_pk_bf16_f32 v3, v24, v25
	s_nop 0
	v_cvt_pk_bf16_f32 v4, v10, v11
	v_cvt_pk_bf16_f32 v5, v12, v13
	global_store_dwordx4 v[14:15], v[2:5], off offset:16
	s_barrier
	s_and_saveexec_b64 s[10:11], s[0:1]
	s_cbranch_execz .LBB0_1358
	s_mov_b64 s[16:17], exec
	v_mbcnt_lo_u32_b32 v2, s16, 0
	v_mbcnt_hi_u32_b32 v2, s17, v2
	v_cmp_eq_u32_e64 s[8:9], 0, v2
	s_and_saveexec_b64 s[12:13], s[8:9]
	s_cbranch_execz .LBB0_1357
	s_bcnt1_i32_b64 s8, s[16:17]
	v_mov_b32_e32 v3, s8
	v_mov_b32_e32 v3, v255
	s_branch .LBB0_1357

; #define NEXT_UNIT() do { __syncthreads(); if (tid == 0) *UQ = (int)__hip_atomic_fetch_add(qctr, 1u, __ATOMIC_RELAXED, __HIP_MEMORY_SCOPE_AGENT); __syncthreads(); u = __builtin_amdgcn_readfirstlane(*UQ); } while (0)
; DI void p5_run(const Args& a, LAS unsigned char* lds, unsigned* qctr, const XcdBarrier& fb, unsigned* F4a, unsigned* F4b) {
;     ...
;         while (u < B3) { const int v = (u - B2) % 256; mlstm_unit(a, lds, (v & 31) >> 2, v & 3, 7 - (v >> 5)); NEXT_UNIT(); }
.LBB0_2094:
	v_readfirstlane_b32 s100, v0
	s_cmp_lg_u32 s100, 0
	s_cbranch_scc1 .Lnuq_mlstm
	v_readlane_b32 s100, v254, 45
	v_readlane_b32 s101, v254, 46
	s_mov_b64 exec, 1
	v_mov_b32_e32 v255, 1
	s_nop 3
	global_atomic_add v255, v0, v255, s[100:101] offset:256 sc0
	s_mov_b64 exec, -1

; DI void mlstm_unit(const Args& a, LAS unsigned char* lds, int b, int h, int J) {
;     ...
;     den += __shfl_xor(den, 32);
;     const float inv = 1.f / fmaxf(fabsf(den), __expf(-mt));
;     float s1 = 0.f;
; #pragma unroll
;     for (int db = 0; db < 4; ++db)
; #pragma unroll
;         for (int reg = 0; reg < 16; ++reg) { O[db][reg] *= inv; s1 += O[db][reg]; }
;     s1 += __shfl_xor(s1, 32);
.LBB0_2119:
	v_and_b32_e32 v68, 64, v1
	v_xor_b32_e32 v2, 32, v1
	v_add_u32_e32 v68, 64, v68
	v_cmp_lt_i32_e32 vcc, v2, v68
	v_mul_f32_e32 v68, 0xbfb8aa3b, v157
	v_exp_f32_e32 v68, v68
	v_cndmask_b32_e32 v2, v1, v2, vcc
	v_lshlrev_b32_e32 v91, 2, v2
	ds_bpermute_b32 v2, v91, v167
	v_lshl_add_u64 v[80:81], s[8:9], 0, v[154:155]
	s_mov_b32 s17, s11
	v_lshl_add_u64 v[80:81], v[80:81], 0, s[16:17]
	s_waitcnt lgkmcnt(0)
	v_add_f32_e32 v2, v167, v2
	v_max_f32_e64 v2, |v2|, v68
	v_div_scale_f32 v68, s[0:1], v2, v2, 1.0
	v_rcp_f32_e32 v69, v68
	v_div_scale_f32 v70, vcc, 1.0, v2, 1.0
	s_lshl_b32 s0, s48, 2
	v_fma_f32 v71, -v68, v69, 1.0
	v_fmac_f32_e32 v69, v71, v69
	v_mul_f32_e32 v71, v70, v69
	v_fma_f32 v72, -v68, v71, v70
	v_fmac_f32_e32 v71, v72, v69
	v_fma_f32 v68, -v68, v71, v70
	v_div_fmas_f32 v68, v68, v69, v71
	v_div_fixup_f32 v70, v68, v2, 1.0
	v_pk_mul_f32 v[68:69], v[58:59], v[70:71] op_sel_hi:[1,0]
	v_pk_mul_f32 v[72:73], v[60:61], v[70:71] op_sel_hi:[1,0]
	v_pk_mul_f32 v[74:75], v[62:63], v[70:71] op_sel_hi:[1,0]
	v_pk_mul_f32 v[76:77], v[64:65], v[70:71] op_sel_hi:[1,0]
	v_pk_mul_f32 v[78:79], v[66:67], v[70:71] op_sel_hi:[1,0]
	v_lshlrev_b32_e32 v71, 2, v166
	v_pk_mul_f32 v[84:85], v[4:5], v[70:71] op_sel_hi:[1,0]
	v_pk_mul_f32 v[82:83], v[6:7], v[70:71] op_sel_hi:[1,0]
	v_add_f32_e32 v2, 0, v84
	v_add_f32_e32 v2, v85, v2
	v_add_f32_e32 v2, v82, v2
	v_add_f32_e32 v2, v83, v2
	v_pk_mul_f32 v[84:85], v[8:9], v[70:71] op_sel_hi:[1,0]
	v_pk_mul_f32 v[82:83], v[10:11], v[70:71] op_sel_hi:[1,0]
	v_add_f32_e32 v2, v84, v2
	v_add_f32_e32 v2, v85, v2
	v_add_f32_e32 v2, v82, v2
	v_add_f32_e32 v2, v83, v2
	v_pk_mul_f32 v[84:85], v[12:13], v[70:71] op_sel_hi:[1,0]
	v_pk_mul_f32 v[82:83], v[14:15], v[70:71] op_sel_hi:[1,0]
	v_add_f32_e32 v2, v84, v2
	v_add_f32_e32 v2, v85, v2
	v_add_f32_e32 v2, v82, v2
	v_add_f32_e32 v2, v83, v2
	v_pk_mul_f32 v[84:85], v[16:17], v[70:71] op_sel_hi:[1,0]
	v_pk_mul_f32 v[82:83], v[18:19], v[70:71] op_sel_hi:[1,0]
	v_add_f32_e32 v2, v84, v2
	v_add_f32_e32 v2, v85, v2
	v_add_f32_e32 v2, v82, v2
	v_add_f32_e32 v2, v83, v2
	v_pk_mul_f32 v[84:85], v[20:21], v[70:71] op_sel_hi:[1,0]
	v_pk_mul_f32 v[82:83], v[22:23], v[70:71] op_sel_hi:[1,0]
	v_add_f32_e32 v2, v84, v2
	v_add_f32_e32 v2, v85, v2
	v_add_f32_e32 v2, v82, v2
	v_add_f32_e32 v2, v83, v2
	v_pk_mul_f32 v[84:85], v[24:25], v[70:71] op_sel_hi:[1,0]
	v_pk_mul_f32 v[82:83], v[26:27], v[70:71] op_sel_hi:[1,0]
	v_add_f32_e32 v2, v84, v2
	v_add_f32_e32 v2, v85, v2
	v_add_f32_e32 v2, v82, v2
	v_add_f32_e32 v2, v83, v2
	v_pk_mul_f32 v[84:85], v[28:29], v[70:71] op_sel_hi:[1,0]
	v_pk_mul_f32 v[82:83], v[30:31], v[70:71] op_sel_hi:[1,0]
	v_add_f32_e32 v2, v84, v2
	v_add_f32_e32 v2, v85, v2
	v_add_f32_e32 v2, v82, v2
	v_add_f32_e32 v2, v83, v2
	v_pk_mul_f32 v[84:85], v[32:33], v[70:71] op_sel_hi:[1,0]
	v_pk_mul_f32 v[82:83], v[34:35], v[70:71] op_sel_hi:[1,0]
	v_add_f32_e32 v2, v84, v2
	v_add_f32_e32 v2, v85, v2
	v_add_f32_e32 v2, v82, v2
	v_add_f32_e32 v2, v83, v2
	v_pk_mul_f32 v[84:85], v[36:37], v[70:71] op_sel_hi:[1,0]
	v_pk_mul_f32 v[82:83], v[38:39], v[70:71] op_sel_hi:[1,0]
	v_add_f32_e32 v2, v84, v2
	v_add_f32_e32 v2, v85, v2
	v_add_f32_e32 v2, v82, v2
	v_add_f32_e32 v2, v83, v2
	v_pk_mul_f32 v[84:85], v[40:41], v[70:71] op_sel_hi:[1,0]
	v_pk_mul_f32 v[82:83], v[42:43], v[70:71] op_sel_hi:[1,0]
	v_add_f32_e32 v2, v84, v2
	v_add_f32_e32 v2, v85, v2
	v_add_f32_e32 v2, v82, v2
	v_add_f32_e32 v2, v83, v2
	v_pk_mul_f32 v[84:85], v[44:45], v[70:71] op_sel_hi:[1,0]
	v_pk_mul_f32 v[82:83], v[46:47], v[70:71] op_sel_hi:[1,0]
	v_add_f32_e32 v2, v84, v2
	v_add_f32_e32 v2, v85, v2
	v_add_f32_e32 v2, v82, v2
	v_add_f32_e32 v2, v83, v2
	v_pk_mul_f32 v[84:85], v[48:49], v[70:71] op_sel_hi:[1,0]
	v_pk_mul_f32 v[82:83], v[50:51], v[70:71] op_sel_hi:[1,0]
	v_add_f32_e32 v2, v84, v2
	v_add_f32_e32 v2, v85, v2
	v_add_f32_e32 v2, v82, v2
	v_add_f32_e32 v2, v83, v2
	v_pk_mul_f32 v[84:85], v[52:53], v[70:71] op_sel_hi:[1,0]
	v_pk_mul_f32 v[82:83], v[54:55], v[70:71] op_sel_hi:[1,0]
	v_add_f32_e32 v2, v84, v2
	v_add_f32_e32 v2, v85, v2
	v_add_f32_e32 v2, v82, v2
	v_add_f32_e32 v2, v83, v2
	v_pk_mul_f32 v[82:83], v[56:57], v[70:71] op_sel_hi:[1,0]
	v_readlane_b32 s48, v253, 55
	v_add_f32_e32 v2, v82, v2
	v_add_f32_e32 v2, v83, v2
	v_add_f32_e32 v2, v68, v2
	v_add_f32_e32 v2, v69, v2
	v_add_f32_e32 v2, v72, v2
	v_add_f32_e32 v2, v73, v2
	v_add_f32_e32 v2, v74, v2
	v_add_f32_e32 v2, v75, v2
	v_add_f32_e32 v2, v76, v2
	v_add_f32_e32 v2, v77, v2
	v_add_f32_e32 v2, v78, v2
	v_add_f32_e32 v72, v79, v2
	ds_bpermute_b32 v73, v91, v72
	v_lshlrev_b32_e32 v2, 1, v166
	v_lshl_add_u64 v[68:69], v[80:81], 0, v[2:3]
	v_readlane_b32 s56, v253, 63
	v_readlane_b32 s57, v254, 0
	s_waitcnt lgkmcnt(0)
; DI void mlstm_unit(const Args& a, LAS unsigned char* lds, int b, int h, int J) {
;     ...
;     s1 += __shfl_xor(s1, 32);
;     const float mu = s1 * (1.f / 128.f);
;     float s2 = 0.f;
; #pragma unroll
;     for (int db = 0; db < 4; ++db)
; #pragma unroll
;         for (int reg = 0; reg < 16; ++reg) { const float dlt = O[db][reg] - mu; s2 += dlt * dlt; }
;     s2 += __shfl_xor(s2, 32);
;     const float rstd = 1.f / sqrtf(s2 * (1.f / 128.f) + EPS);
;     const float* gn = INF(a, I_GNORM) + h * 128; const bf16_t* ob = (const bf16_t*)(ws + WS_OB) + row * 512 + h * 128; bf16_t* op = (bf16_t*)(ws + WS_OAHB) + row * 1024 + 512 + h * 128;
	v_add_f32_e32 v72, v72, v73
	v_mul_f32_e32 v90, 0x3c000000, v72
	v_pk_fma_f32 v[92:93], v[4:5], v[70:71], v[90:91] op_sel_hi:[1,0,0] neg_lo:[0,0,1] neg_hi:[0,0,1]
	v_pk_fma_f32 v[96:97], v[6:7], v[70:71], v[90:91] op_sel_hi:[1,0,0] neg_lo:[0,0,1] neg_hi:[0,0,1]
	v_pk_mul_f32 v[94:95], v[92:93], v[92:93]
	v_pk_mul_f32 v[98:99], v[96:97], v[96:97]
	v_pk_fma_f32 v[100:101], v[8:9], v[70:71], v[90:91] op_sel_hi:[1,0,0] neg_lo:[0,0,1] neg_hi:[0,0,1]
	v_pk_fma_f32 v[104:105], v[10:11], v[70:71], v[90:91] op_sel_hi:[1,0,0] neg_lo:[0,0,1] neg_hi:[0,0,1]
	v_pk_fma_f32 v[108:109], v[12:13], v[70:71], v[90:91] op_sel_hi:[1,0,0] neg_lo:[0,0,1] neg_hi:[0,0,1]
	v_pk_fma_f32 v[112:113], v[14:15], v[70:71], v[90:91] op_sel_hi:[1,0,0] neg_lo:[0,0,1] neg_hi:[0,0,1]
	v_pk_fma_f32 v[116:117], v[16:17], v[70:71], v[90:91] op_sel_hi:[1,0,0] neg_lo:[0,0,1] neg_hi:[0,0,1]
	v_pk_fma_f32 v[120:121], v[18:19], v[70:71], v[90:91] op_sel_hi:[1,0,0] neg_lo:[0,0,1] neg_hi:[0,0,1]
	v_pk_fma_f32 v[124:125], v[20:21], v[70:71], v[90:91] op_sel_hi:[1,0,0] neg_lo:[0,0,1] neg_hi:[0,0,1]
	v_pk_fma_f32 v[126:127], v[22:23], v[70:71], v[90:91] op_sel_hi:[1,0,0] neg_lo:[0,0,1] neg_hi:[0,0,1]
	v_pk_fma_f32 v[82:83], v[24:25], v[70:71], v[90:91] op_sel_hi:[1,0,0] neg_lo:[0,0,1] neg_hi:[0,0,1]
	v_pk_fma_f32 v[80:81], v[26:27], v[70:71], v[90:91] op_sel_hi:[1,0,0] neg_lo:[0,0,1] neg_hi:[0,0,1]
	v_pk_fma_f32 v[78:79], v[28:29], v[70:71], v[90:91] op_sel_hi:[1,0,0] neg_lo:[0,0,1] neg_hi:[0,0,1]
	v_pk_fma_f32 v[76:77], v[30:31], v[70:71], v[90:91] op_sel_hi:[1,0,0] neg_lo:[0,0,1] neg_hi:[0,0,1]
	v_pk_fma_f32 v[74:75], v[32:33], v[70:71], v[90:91] op_sel_hi:[1,0,0] neg_lo:[0,0,1] neg_hi:[0,0,1]
	v_pk_fma_f32 v[72:73], v[34:35], v[70:71], v[90:91] op_sel_hi:[1,0,0] neg_lo:[0,0,1] neg_hi:[0,0,1]
	v_pk_fma_f32 v[34:35], v[36:37], v[70:71], v[90:91] op_sel_hi:[1,0,0] neg_lo:[0,0,1] neg_hi:[0,0,1]
	v_pk_fma_f32 v[36:37], v[38:39], v[70:71], v[90:91] op_sel_hi:[1,0,0] neg_lo:[0,0,1] neg_hi:[0,0,1]
	v_pk_fma_f32 v[30:31], v[40:41], v[70:71], v[90:91] op_sel_hi:[1,0,0] neg_lo:[0,0,1] neg_hi:[0,0,1]
	v_pk_fma_f32 v[32:33], v[42:43], v[70:71], v[90:91] op_sel_hi:[1,0,0] neg_lo:[0,0,1] neg_hi:[0,0,1]
	v_pk_fma_f32 v[26:27], v[44:45], v[70:71], v[90:91] op_sel_hi:[1,0,0] neg_lo:[0,0,1] neg_hi:[0,0,1]
	v_pk_fma_f32 v[28:29], v[46:47], v[70:71], v[90:91] op_sel_hi:[1,0,0] neg_lo:[0,0,1] neg_hi:[0,0,1]
	v_pk_fma_f32 v[22:23], v[48:49], v[70:71], v[90:91] op_sel_hi:[1,0,0] neg_lo:[0,0,1] neg_hi:[0,0,1]
	v_pk_fma_f32 v[24:25], v[50:51], v[70:71], v[90:91] op_sel_hi:[1,0,0] neg_lo:[0,0,1] neg_hi:[0,0,1]
	v_pk_fma_f32 v[16:17], v[52:53], v[70:71], v[90:91] op_sel_hi:[1,0,0] neg_lo:[0,0,1] neg_hi:[0,0,1]
	v_pk_fma_f32 v[18:19], v[54:55], v[70:71], v[90:91] op_sel_hi:[1,0,0] neg_lo:[0,0,1] neg_hi:[0,0,1]
	v_pk_fma_f32 v[12:13], v[56:57], v[70:71], v[90:91] op_sel_hi:[1,0,0] neg_lo:[0,0,1] neg_hi:[0,0,1]
	v_pk_fma_f32 v[8:9], v[62:63], v[70:71], v[90:91] op_sel_hi:[1,0,0] neg_lo:[0,0,1] neg_hi:[0,0,1]
	v_pk_fma_f32 v[6:7], v[64:65], v[70:71], v[90:91] op_sel_hi:[1,0,0] neg_lo:[0,0,1] neg_hi:[0,0,1]
	v_pk_fma_f32 v[4:5], v[66:67], v[70:71], v[90:91] op_sel_hi:[1,0,0] neg_lo:[0,0,1] neg_hi:[0,0,1]
	v_pk_fma_f32 v[14:15], v[58:59], v[70:71], v[90:91] op_sel_hi:[1,0,0] neg_lo:[0,0,1] neg_hi:[0,0,1]
	v_pk_fma_f32 v[10:11], v[60:61], v[70:71], v[90:91] op_sel_hi:[1,0,0] neg_lo:[0,0,1] neg_hi:[0,0,1]
	v_add_f32_e32 v70, v94, v95
	v_add_f32_e32 v70, v98, v70
	v_pk_mul_f32 v[102:103], v[100:101], v[100:101]
	v_add_f32_e32 v70, v99, v70
	v_add_f32_e32 v70, v102, v70
	v_pk_mul_f32 v[106:107], v[104:105], v[104:105]
	v_add_f32_e32 v70, v103, v70
	v_add_f32_e32 v70, v106, v70
	v_pk_mul_f32 v[110:111], v[108:109], v[108:109]
	v_add_f32_e32 v70, v107, v70
	v_add_f32_e32 v70, v110, v70
	v_pk_mul_f32 v[114:115], v[112:113], v[112:113]
	v_add_f32_e32 v70, v111, v70
	v_add_f32_e32 v70, v114, v70
	v_pk_mul_f32 v[118:119], v[116:117], v[116:117]
	v_add_f32_e32 v70, v115, v70
	v_add_f32_e32 v70, v118, v70
	v_pk_mul_f32 v[122:123], v[120:121], v[120:121]
	v_add_f32_e32 v70, v119, v70
	v_add_f32_e32 v70, v122, v70
	v_pk_mul_f32 v[20:21], v[124:125], v[124:125]
	v_add_f32_e32 v70, v123, v70
	v_add_f32_e32 v20, v20, v70
	s_mov_b64 s[20:21], s[56:57]
	v_pk_mul_f32 v[128:129], v[126:127], v[126:127]
	v_add_f32_e32 v20, v21, v20
	s_add_u32 s0, s20, s0
	v_add_f32_e32 v20, v128, v20
	s_addc_u32 s1, s21, 0
	v_pk_mul_f32 v[130:131], v[82:83], v[82:83]
	v_add_f32_e32 v20, v129, v20
	global_load_dwordx4 v[84:87], v71, s[0:1]
	global_load_dwordx2 v[88:89], v[68:69], off
	v_add_f32_e32 v20, v130, v20
	s_waitcnt vmcnt(5)
	v_pk_mul_f32 v[132:133], v[80:81], v[80:81]
	v_add_f32_e32 v20, v131, v20
	v_add_f32_e32 v20, v132, v20
	v_pk_mul_f32 v[134:135], v[78:79], v[78:79]
	v_add_f32_e32 v20, v133, v20
	v_add_f32_e32 v20, v134, v20
	s_waitcnt vmcnt(4)
	v_pk_mul_f32 v[136:137], v[76:77], v[76:77]
	v_add_f32_e32 v20, v135, v20
	v_add_f32_e32 v20, v136, v20
	v_pk_mul_f32 v[138:139], v[74:75], v[74:75]
	v_add_f32_e32 v20, v137, v20
	v_add_f32_e32 v20, v138, v20
	s_waitcnt vmcnt(3)
; DI unsigned pk2(float lo, float hi) { f32x2 v = {lo, hi}; bf16x2_t b = __builtin_convertvector(v, bf16x2_t); return __builtin_bit_cast(unsigned, b); }
; DI f32x4 ld4bf(const bf16_t* p) { const u32x2 w = *(const u32x2*)p; f32x4 o; o.x = bf2f(w.x & 0xffffu); o.y = bf2f(w.x >> 16); o.z = bf2f(w.y & 0xffffu); o.w = bf2f(w.y >> 16); return o; }
; DI void mlstm_unit(const Args& a, LAS unsigned char* lds, int b, int h, int J) {
;     ...
;     s2 += __shfl_xor(s2, 32);
;     const float rstd = 1.f / sqrtf(s2 * (1.f / 128.f) + EPS);
;     const float* gn = INF(a, I_GNORM) + h * 128; const bf16_t* ob = (const bf16_t*)(ws + WS_OB) + row * 512 + h * 128; bf16_t* op = (bf16_t*)(ws + WS_OAHB) + row * 1024 + 512 + h * 128;
; #pragma unroll
;     for (int db = 0; db < 4; ++db)
; #pragma unroll
;         for (int rg = 0; rg < 4; ++rg) { const int dv = 32 * db + 8 * rg + 4 * h2; const f32x4 g4 = *(const f32x4*)(gn + dv), o4 = ld4bf(ob + dv);
;             u32x2 w; w.x = pk2((O[db][4 * rg] - mu) * rstd * g4.x * o4.x, (O[db][4 * rg + 1] - mu) * rstd * g4.y * o4.y);
;             w.y = pk2((O[db][4 * rg + 2] - mu) * rstd * g4.z * o4.z, (O[db][4 * rg + 3] - mu) * rstd * g4.w * o4.w); *(u32x2*)(op + dv) = w; }
	v_pk_mul_f32 v[140:141], v[72:73], v[72:73]
	v_add_f32_e32 v20, v139, v20
	v_add_f32_e32 v20, v140, v20
	v_pk_mul_f32 v[142:143], v[34:35], v[34:35]
	v_add_f32_e32 v20, v141, v20
	v_add_f32_e32 v20, v142, v20
	v_pk_mul_f32 v[38:39], v[36:37], v[36:37]
	v_add_f32_e32 v20, v143, v20
	v_add_f32_e32 v20, v38, v20
	v_pk_mul_f32 v[40:41], v[30:31], v[30:31]
	v_add_f32_e32 v20, v39, v20
	v_add_f32_e32 v20, v40, v20
	v_pk_mul_f32 v[42:43], v[32:33], v[32:33]
	v_add_f32_e32 v20, v41, v20
	v_add_f32_e32 v20, v42, v20
	v_pk_mul_f32 v[44:45], v[26:27], v[26:27]
	v_add_f32_e32 v20, v43, v20
	v_add_f32_e32 v20, v44, v20
	v_pk_mul_f32 v[46:47], v[28:29], v[28:29]
	v_add_f32_e32 v20, v45, v20
	v_add_f32_e32 v20, v46, v20
	v_pk_mul_f32 v[48:49], v[22:23], v[22:23]
	v_add_f32_e32 v20, v47, v20
	v_add_f32_e32 v20, v48, v20
	v_pk_mul_f32 v[50:51], v[24:25], v[24:25]
	v_add_f32_e32 v20, v49, v20
	v_add_f32_e32 v20, v50, v20
	v_pk_mul_f32 v[52:53], v[16:17], v[16:17]
	v_add_f32_e32 v20, v51, v20
	v_add_f32_e32 v20, v52, v20
	v_pk_mul_f32 v[54:55], v[18:19], v[18:19]
	v_add_f32_e32 v20, v53, v20
	v_add_f32_e32 v20, v54, v20
	v_pk_mul_f32 v[56:57], v[12:13], v[12:13]
	v_add_f32_e32 v20, v55, v20
	v_add_f32_e32 v20, v56, v20
	v_pk_mul_f32 v[58:59], v[14:15], v[14:15]
	v_add_f32_e32 v20, v57, v20
	v_add_f32_e32 v20, v58, v20
	v_pk_mul_f32 v[60:61], v[10:11], v[10:11]
	v_add_f32_e32 v20, v59, v20
	v_add_f32_e32 v20, v60, v20
	v_pk_mul_f32 v[62:63], v[8:9], v[8:9]
	v_add_f32_e32 v20, v61, v20
	v_add_f32_e32 v20, v62, v20
	v_pk_mul_f32 v[64:65], v[6:7], v[6:7]
	v_add_f32_e32 v20, v63, v20
	v_add_f32_e32 v20, v64, v20
	v_pk_mul_f32 v[66:67], v[4:5], v[4:5]
	v_add_f32_e32 v20, v65, v20
	v_add_f32_e32 v20, v66, v20
	v_add_f32_e32 v38, v67, v20
	ds_bpermute_b32 v39, v91, v38
	v_lshlrev_b64 v[20:21], 11, v[152:153]
	v_lshl_add_u64 v[20:21], s[94:95], 0, v[20:21]
	v_lshl_add_u64 v[20:21], v[20:21], 0, s[16:17]
	v_lshl_add_u64 v[20:21], v[20:21], 0, v[2:3]
	s_waitcnt lgkmcnt(0)
	v_add_f32_e32 v38, v38, v39
	v_fmamk_f32 v38, v38, 0x3c000000, v164
	v_mul_f32_e32 v39, 0x4f800000, v38
	v_cmp_gt_f32_e32 vcc, s45, v38
	global_load_dwordx2 v[42:43], v[68:69], off offset:16
	global_load_dwordx2 v[44:45], v[68:69], off offset:32
	global_load_dwordx2 v[46:47], v[68:69], off offset:48
	v_cndmask_b32_e32 v40, v38, v39, vcc
	v_sqrt_f32_e32 v41, v40
	v_readlane_b32 s49, v253, 56
	v_readlane_b32 s50, v253, 57
	s_waitcnt vmcnt(3)
	v_lshlrev_b32_e32 v38, 16, v89
	v_add_u32_e32 v48, -1, v41
	v_fma_f32 v49, -v48, v41, v40
	v_cmp_ge_f32_e64 s[2:3], 0, v49
	v_add_u32_e32 v49, 1, v41
	v_and_b32_e32 v39, 0xffff0000, v89
	v_cndmask_b32_e64 v48, v41, v48, s[2:3]
	v_fma_f32 v41, -v49, v41, v40
	v_cmp_lt_f32_e64 s[2:3], 0, v41
	v_readlane_b32 s51, v253, 58
	v_readlane_b32 s52, v253, 59
	v_cndmask_b32_e64 v41, v48, v49, s[2:3]
	v_mul_f32_e32 v48, 0x37800000, v41
	v_cndmask_b32_e32 v41, v41, v48, vcc
	v_cmp_class_f32_e32 vcc, v40, v165
	v_readlane_b32 s53, v253, 60
	v_readlane_b32 s54, v253, 61
	v_cndmask_b32_e32 v48, v41, v40, vcc
	v_div_scale_f32 v49, s[2:3], v48, v48, 1.0
	v_rcp_f32_e32 v50, v49
	v_lshlrev_b32_e32 v40, 16, v88
	v_and_b32_e32 v41, 0xffff0000, v88
	v_readlane_b32 s55, v253, 62
	v_fma_f32 v2, -v49, v50, 1.0
	v_fmac_f32_e32 v50, v2, v50
	v_div_scale_f32 v2, vcc, 1.0, v48, 1.0
	v_mul_f32_e32 v51, v2, v50
	v_fma_f32 v52, -v49, v51, v2
	v_fmac_f32_e32 v51, v52, v50
	v_fma_f32 v2, -v49, v51, v2
	v_div_fmas_f32 v2, v2, v50, v51
	v_div_fixup_f32 v2, v2, v48, 1.0
	v_pk_mul_f32 v[48:49], v[92:93], v[2:3] op_sel_hi:[1,0]
	v_pk_mul_f32 v[54:55], v[126:127], v[2:3] op_sel_hi:[1,0]
	v_pk_mul_f32 v[48:49], v[84:85], v[48:49]
	v_pk_mul_f32 v[34:35], v[34:35], v[2:3] op_sel_hi:[1,0]
	v_pk_mul_f32 v[40:41], v[48:49], v[40:41]
	v_pk_mul_f32 v[48:49], v[96:97], v[2:3] op_sel_hi:[1,0]
	v_cvt_pk_bf16_f32 v40, v40, v41
	v_pk_mul_f32 v[48:49], v[86:87], v[48:49]
	v_pk_mul_f32 v[36:37], v[36:37], v[2:3] op_sel_hi:[1,0]
	v_pk_mul_f32 v[38:39], v[48:49], v[38:39]
	v_pk_mul_f32 v[30:31], v[30:31], v[2:3] op_sel_hi:[1,0]
	v_cvt_pk_bf16_f32 v41, v38, v39
	v_add_co_u32_e32 v38, vcc, s46, v20
	v_pk_mul_f32 v[32:33], v[32:33], v[2:3] op_sel_hi:[1,0]
	s_nop 0
	v_addc_co_u32_e32 v39, vcc, 0, v21, vcc
	global_store_dwordx2 v[38:39], v[40:41], off offset:3072
	global_load_dwordx4 v[38:41], v71, s[0:1] offset:32
	v_lshl_add_u64 v[20:21], v[20:21], 0, s[14:15]
	v_pk_mul_f32 v[26:27], v[26:27], v[2:3] op_sel_hi:[1,0]
	v_pk_mul_f32 v[28:29], v[28:29], v[2:3] op_sel_hi:[1,0]
	v_pk_mul_f32 v[22:23], v[22:23], v[2:3] op_sel_hi:[1,0]
	v_pk_mul_f32 v[24:25], v[24:25], v[2:3] op_sel_hi:[1,0]
	v_pk_mul_f32 v[16:17], v[16:17], v[2:3] op_sel_hi:[1,0]
	v_pk_mul_f32 v[18:19], v[18:19], v[2:3] op_sel_hi:[1,0]
	v_pk_mul_f32 v[12:13], v[12:13], v[2:3] op_sel_hi:[1,0]
	v_pk_mul_f32 v[14:15], v[14:15], v[2:3] op_sel_hi:[1,0]
	v_pk_mul_f32 v[10:11], v[10:11], v[2:3] op_sel_hi:[1,0]
	v_pk_mul_f32 v[8:9], v[8:9], v[2:3] op_sel_hi:[1,0]
	v_pk_mul_f32 v[6:7], v[6:7], v[2:3] op_sel_hi:[1,0]
	v_pk_mul_f32 v[4:5], v[4:5], v[2:3] op_sel_hi:[1,0]
	v_readlane_b32 s58, v254, 1
	v_readlane_b32 s59, v254, 2
	v_readlane_b32 s60, v254, 3
	v_readlane_b32 s61, v254, 4
	v_readlane_b32 s62, v254, 5
	v_readlane_b32 s63, v254, 6
	s_waitcnt vmcnt(4)
	v_lshlrev_b32_e32 v48, 16, v43
	v_and_b32_e32 v49, 0xffff0000, v43
	v_lshlrev_b32_e32 v50, 16, v42
	v_and_b32_e32 v51, 0xffff0000, v42
	v_pk_mul_f32 v[42:43], v[100:101], v[2:3] op_sel_hi:[1,0]
	s_waitcnt vmcnt(0)
; DI unsigned pk2(float lo, float hi) { f32x2 v = {lo, hi}; bf16x2_t b = __builtin_convertvector(v, bf16x2_t); return __builtin_bit_cast(unsigned, b); }
; DI f32x4 ld4bf(const bf16_t* p) { const u32x2 w = *(const u32x2*)p; f32x4 o; o.x = bf2f(w.x & 0xffffu); o.y = bf2f(w.x >> 16); o.z = bf2f(w.y & 0xffffu); o.w = bf2f(w.y >> 16); return o; }
; DI void mlstm_unit(const Args& a, LAS unsigned char* lds, int b, int h, int J) {
;     ...
; #pragma unroll
;     for (int db = 0; db < 4; ++db)
; #pragma unroll
;         for (int rg = 0; rg < 4; ++rg) { const int dv = 32 * db + 8 * rg + 4 * h2; const f32x4 g4 = *(const f32x4*)(gn + dv), o4 = ld4bf(ob + dv);
;             u32x2 w; w.x = pk2((O[db][4 * rg] - mu) * rstd * g4.x * o4.x, (O[db][4 * rg + 1] - mu) * rstd * g4.y * o4.y);
;             w.y = pk2((O[db][4 * rg + 2] - mu) * rstd * g4.z * o4.z, (O[db][4 * rg + 3] - mu) * rstd * g4.w * o4.w); *(u32x2*)(op + dv) = w; }
	v_pk_mul_f32 v[38:39], v[38:39], v[42:43]
	v_pk_mul_f32 v[42:43], v[104:105], v[2:3] op_sel_hi:[1,0]
	v_pk_mul_f32 v[38:39], v[38:39], v[50:51]
	v_pk_mul_f32 v[40:41], v[40:41], v[42:43]
	v_cvt_pk_bf16_f32 v38, v38, v39
	v_pk_mul_f32 v[40:41], v[40:41], v[48:49]
	v_lshlrev_b32_e32 v42, 16, v45
	v_cvt_pk_bf16_f32 v39, v40, v41
	global_store_dwordx2 v[20:21], v[38:39], off offset:16
	global_load_dwordx4 v[38:41], v71, s[0:1] offset:64
	v_and_b32_e32 v43, 0xffff0000, v45
	v_lshlrev_b32_e32 v48, 16, v44
	v_and_b32_e32 v49, 0xffff0000, v44
	v_pk_mul_f32 v[44:45], v[108:109], v[2:3] op_sel_hi:[1,0]
	v_pk_mul_f32 v[50:51], v[112:113], v[2:3] op_sel_hi:[1,0]
	s_waitcnt vmcnt(0)
	v_pk_mul_f32 v[38:39], v[38:39], v[44:45]
	v_pk_mul_f32 v[40:41], v[40:41], v[50:51]
	v_pk_mul_f32 v[38:39], v[38:39], v[48:49]
	v_pk_mul_f32 v[40:41], v[40:41], v[42:43]
	v_cvt_pk_bf16_f32 v38, v38, v39
	v_cvt_pk_bf16_f32 v39, v40, v41
	global_store_dwordx2 v[20:21], v[38:39], off offset:32
	global_load_dwordx4 v[38:41], v71, s[0:1] offset:96
	s_nop 0
	global_load_dwordx2 v[42:43], v[68:69], off offset:64
	v_lshlrev_b32_e32 v44, 16, v47
	v_and_b32_e32 v45, 0xffff0000, v47
	v_lshlrev_b32_e32 v48, 16, v46
	v_and_b32_e32 v49, 0xffff0000, v46
	v_pk_mul_f32 v[46:47], v[116:117], v[2:3] op_sel_hi:[1,0]
	v_pk_mul_f32 v[50:51], v[120:121], v[2:3] op_sel_hi:[1,0]
	s_waitcnt vmcnt(1)
	v_pk_mul_f32 v[38:39], v[38:39], v[46:47]
	v_pk_mul_f32 v[40:41], v[40:41], v[50:51]
	v_pk_mul_f32 v[38:39], v[38:39], v[48:49]
	v_pk_mul_f32 v[40:41], v[40:41], v[44:45]
	v_cvt_pk_bf16_f32 v38, v38, v39
	v_cvt_pk_bf16_f32 v39, v40, v41
	global_store_dwordx2 v[20:21], v[38:39], off offset:48
	global_load_dwordx4 v[38:41], v71, s[0:1] offset:128
	s_nop 0
	global_load_dwordx2 v[44:45], v[68:69], off offset:80
	global_load_dwordx2 v[46:47], v[68:69], off offset:96
	global_load_dwordx2 v[48:49], v[68:69], off offset:112
	s_waitcnt vmcnt(5)
	v_lshlrev_b32_e32 v50, 16, v43
	v_and_b32_e32 v51, 0xffff0000, v43
	v_lshlrev_b32_e32 v52, 16, v42
	v_and_b32_e32 v53, 0xffff0000, v42
	v_pk_mul_f32 v[42:43], v[124:125], v[2:3] op_sel_hi:[1,0]
	s_waitcnt vmcnt(3)
	v_pk_mul_f32 v[40:41], v[40:41], v[54:55]
	v_pk_mul_f32 v[38:39], v[38:39], v[42:43]
	v_pk_mul_f32 v[40:41], v[40:41], v[50:51]
	v_pk_mul_f32 v[38:39], v[38:39], v[52:53]
	s_waitcnt vmcnt(2)
	v_lshlrev_b32_e32 v42, 16, v45
	v_cvt_pk_bf16_f32 v38, v38, v39
	v_cvt_pk_bf16_f32 v39, v40, v41
	global_store_dwordx2 v[20:21], v[38:39], off offset:64
	global_load_dwordx4 v[38:41], v71, s[0:1] offset:160
	v_and_b32_e32 v43, 0xffff0000, v45
	v_lshlrev_b32_e32 v50, 16, v44
	v_and_b32_e32 v51, 0xffff0000, v44
	v_pk_mul_f32 v[44:45], v[82:83], v[2:3] op_sel_hi:[1,0]
	v_pk_mul_f32 v[52:53], v[80:81], v[2:3] op_sel_hi:[1,0]
	s_waitcnt vmcnt(0)
	v_pk_mul_f32 v[38:39], v[38:39], v[44:45]
	v_pk_mul_f32 v[40:41], v[40:41], v[52:53]
	v_pk_mul_f32 v[38:39], v[38:39], v[50:51]
	v_pk_mul_f32 v[40:41], v[40:41], v[42:43]
	v_cvt_pk_bf16_f32 v38, v38, v39
	v_cvt_pk_bf16_f32 v39, v40, v41
	global_store_dwordx2 v[20:21], v[38:39], off offset:80
	global_load_dwordx4 v[38:41], v71, s[0:1] offset:192
	v_lshlrev_b32_e32 v42, 16, v47
	v_and_b32_e32 v43, 0xffff0000, v47
	v_lshlrev_b32_e32 v44, 16, v46
	v_and_b32_e32 v45, 0xffff0000, v46
	v_pk_mul_f32 v[46:47], v[78:79], v[2:3] op_sel_hi:[1,0]
	v_pk_mul_f32 v[50:51], v[76:77], v[2:3] op_sel_hi:[1,0]
	s_waitcnt vmcnt(0)
	v_pk_mul_f32 v[38:39], v[38:39], v[46:47]
	v_pk_mul_f32 v[40:41], v[40:41], v[50:51]
	v_pk_mul_f32 v[38:39], v[38:39], v[44:45]
	v_pk_mul_f32 v[40:41], v[40:41], v[42:43]
	v_cvt_pk_bf16_f32 v38, v38, v39
	v_cvt_pk_bf16_f32 v39, v40, v41
	global_store_dwordx2 v[20:21], v[38:39], off offset:96
	global_load_dwordx4 v[38:41], v71, s[0:1] offset:224
	s_nop 0
	global_load_dwordx2 v[42:43], v[68:69], off offset:128
	v_lshlrev_b32_e32 v44, 16, v49
	v_and_b32_e32 v45, 0xffff0000, v49
	v_lshlrev_b32_e32 v46, 16, v48
	v_and_b32_e32 v47, 0xffff0000, v48
	v_pk_mul_f32 v[48:49], v[74:75], v[2:3] op_sel_hi:[1,0]
	v_pk_mul_f32 v[50:51], v[72:73], v[2:3] op_sel_hi:[1,0]
	s_waitcnt vmcnt(1)
	v_pk_mul_f32 v[38:39], v[38:39], v[48:49]
	v_pk_mul_f32 v[40:41], v[40:41], v[50:51]
	v_pk_mul_f32 v[38:39], v[38:39], v[46:47]
	v_pk_mul_f32 v[40:41], v[40:41], v[44:45]
	v_cvt_pk_bf16_f32 v38, v38, v39
	v_cvt_pk_bf16_f32 v39, v40, v41
	global_store_dwordx2 v[20:21], v[38:39], off offset:112
	global_load_dwordx4 v[38:41], v71, s[0:1] offset:256
	s_nop 0
	global_load_dwordx2 v[44:45], v[68:69], off offset:144
	global_load_dwordx2 v[46:47], v[68:69], off offset:160
	global_load_dwordx2 v[48:49], v[68:69], off offset:176
	s_waitcnt vmcnt(5)
	v_lshlrev_b32_e32 v50, 16, v43
	v_and_b32_e32 v51, 0xffff0000, v43
	v_lshlrev_b32_e32 v52, 16, v42
	v_and_b32_e32 v53, 0xffff0000, v42
	s_waitcnt vmcnt(3)
; DI unsigned pk2(float lo, float hi) { f32x2 v = {lo, hi}; bf16x2_t b = __builtin_convertvector(v, bf16x2_t); return __builtin_bit_cast(unsigned, b); }
; DI f32x4 ld4bf(const bf16_t* p) { const u32x2 w = *(const u32x2*)p; f32x4 o; o.x = bf2f(w.x & 0xffffu); o.y = bf2f(w.x >> 16); o.z = bf2f(w.y & 0xffffu); o.w = bf2f(w.y >> 16); return o; }
; DI void mlstm_unit(const Args& a, LAS unsigned char* lds, int b, int h, int J) {
;     ...
; #pragma unroll
;     for (int db = 0; db < 4; ++db)
; #pragma unroll
;         for (int rg = 0; rg < 4; ++rg) { const int dv = 32 * db + 8 * rg + 4 * h2; const f32x4 g4 = *(const f32x4*)(gn + dv), o4 = ld4bf(ob + dv);
;             u32x2 w; w.x = pk2((O[db][4 * rg] - mu) * rstd * g4.x * o4.x, (O[db][4 * rg + 1] - mu) * rstd * g4.y * o4.y);
;             w.y = pk2((O[db][4 * rg + 2] - mu) * rstd * g4.z * o4.z, (O[db][4 * rg + 3] - mu) * rstd * g4.w * o4.w); *(u32x2*)(op + dv) = w; }
;     __syncthreads();
	v_pk_mul_f32 v[34:35], v[38:39], v[34:35]
	v_pk_mul_f32 v[36:37], v[40:41], v[36:37]
	v_pk_mul_f32 v[34:35], v[34:35], v[52:53]
	v_pk_mul_f32 v[36:37], v[36:37], v[50:51]
	v_cvt_pk_bf16_f32 v34, v34, v35
	v_cvt_pk_bf16_f32 v35, v36, v37
	global_store_dwordx2 v[20:21], v[34:35], off offset:128
	global_load_dwordx4 v[34:37], v71, s[0:1] offset:288
	s_waitcnt vmcnt(4)
	v_lshlrev_b32_e32 v38, 16, v45
	v_and_b32_e32 v39, 0xffff0000, v45
	v_lshlrev_b32_e32 v40, 16, v44
	v_and_b32_e32 v41, 0xffff0000, v44
	s_waitcnt vmcnt(0)
	v_pk_mul_f32 v[30:31], v[34:35], v[30:31]
	v_pk_mul_f32 v[32:33], v[36:37], v[32:33]
	v_pk_mul_f32 v[30:31], v[30:31], v[40:41]
	v_pk_mul_f32 v[32:33], v[32:33], v[38:39]
	v_cvt_pk_bf16_f32 v30, v30, v31
	v_cvt_pk_bf16_f32 v31, v32, v33
	global_store_dwordx2 v[20:21], v[30:31], off offset:144
	global_load_dwordx4 v[30:33], v71, s[0:1] offset:320
	v_lshlrev_b32_e32 v34, 16, v46
	v_and_b32_e32 v35, 0xffff0000, v46
	v_lshlrev_b32_e32 v36, 16, v47
	v_and_b32_e32 v37, 0xffff0000, v47
	s_waitcnt vmcnt(0)
	v_pk_mul_f32 v[26:27], v[30:31], v[26:27]
	v_pk_mul_f32 v[28:29], v[32:33], v[28:29]
	v_pk_mul_f32 v[26:27], v[26:27], v[34:35]
	v_pk_mul_f32 v[28:29], v[28:29], v[36:37]
	v_cvt_pk_bf16_f32 v26, v26, v27
	v_cvt_pk_bf16_f32 v27, v28, v29
	global_store_dwordx2 v[20:21], v[26:27], off offset:160
	global_load_dwordx4 v[26:29], v71, s[0:1] offset:352
	s_nop 0
	global_load_dwordx2 v[30:31], v[68:69], off offset:192
	v_lshlrev_b32_e32 v32, 16, v48
	v_and_b32_e32 v33, 0xffff0000, v48
	v_lshlrev_b32_e32 v34, 16, v49
	v_and_b32_e32 v35, 0xffff0000, v49
	s_waitcnt vmcnt(1)
	v_pk_mul_f32 v[22:23], v[26:27], v[22:23]
	v_pk_mul_f32 v[24:25], v[28:29], v[24:25]
	v_pk_mul_f32 v[22:23], v[22:23], v[32:33]
	v_pk_mul_f32 v[24:25], v[24:25], v[34:35]
	v_cvt_pk_bf16_f32 v22, v22, v23
	v_cvt_pk_bf16_f32 v23, v24, v25
	global_store_dwordx2 v[20:21], v[22:23], off offset:176
	global_load_dwordx4 v[22:25], v71, s[0:1] offset:384
	s_nop 0
	global_load_dwordx2 v[26:27], v[68:69], off offset:208
	global_load_dwordx2 v[28:29], v[68:69], off offset:224
	global_load_dwordx2 v[32:33], v[68:69], off offset:240
	s_waitcnt vmcnt(5)
	v_lshlrev_b32_e32 v34, 16, v30
	v_and_b32_e32 v35, 0xffff0000, v30
	v_lshlrev_b32_e32 v30, 16, v31
	v_and_b32_e32 v31, 0xffff0000, v31
	s_waitcnt vmcnt(3)
	v_pk_mul_f32 v[16:17], v[22:23], v[16:17]
	v_pk_mul_f32 v[18:19], v[24:25], v[18:19]
	v_pk_mul_f32 v[16:17], v[16:17], v[34:35]
	v_pk_mul_f32 v[18:19], v[18:19], v[30:31]
	v_cvt_pk_bf16_f32 v16, v16, v17
	v_cvt_pk_bf16_f32 v17, v18, v19
	global_store_dwordx2 v[20:21], v[16:17], off offset:192
	global_load_dwordx4 v[16:19], v71, s[0:1] offset:416
	s_waitcnt vmcnt(4)
	v_lshlrev_b32_e32 v22, 16, v26
	v_and_b32_e32 v23, 0xffff0000, v26
	v_lshlrev_b32_e32 v24, 16, v27
	v_and_b32_e32 v25, 0xffff0000, v27
	s_waitcnt vmcnt(0)
	v_pk_mul_f32 v[12:13], v[16:17], v[12:13]
	v_pk_mul_f32 v[14:15], v[18:19], v[14:15]
	v_pk_mul_f32 v[12:13], v[12:13], v[22:23]
	v_pk_mul_f32 v[14:15], v[14:15], v[24:25]
	v_cvt_pk_bf16_f32 v12, v12, v13
	v_cvt_pk_bf16_f32 v13, v14, v15
	global_store_dwordx2 v[20:21], v[12:13], off offset:208
	global_load_dwordx4 v[12:15], v71, s[0:1] offset:448
	v_lshlrev_b32_e32 v16, 16, v28
	v_and_b32_e32 v17, 0xffff0000, v28
	v_lshlrev_b32_e32 v18, 16, v29
	v_and_b32_e32 v19, 0xffff0000, v29
	s_waitcnt vmcnt(0)
	v_pk_mul_f32 v[10:11], v[12:13], v[10:11]
	v_pk_mul_f32 v[8:9], v[14:15], v[8:9]
	v_pk_mul_f32 v[10:11], v[10:11], v[16:17]
	v_pk_mul_f32 v[8:9], v[8:9], v[18:19]
	v_cvt_pk_bf16_f32 v10, v10, v11
	v_cvt_pk_bf16_f32 v11, v8, v9
	global_store_dwordx2 v[20:21], v[10:11], off offset:224
	global_load_dwordx4 v[8:11], v71, s[0:1] offset:480
	v_lshlrev_b32_e32 v12, 16, v32
	v_and_b32_e32 v13, 0xffff0000, v32
	v_lshlrev_b32_e32 v14, 16, v33
	v_and_b32_e32 v15, 0xffff0000, v33
	s_waitcnt vmcnt(0)
	v_pk_mul_f32 v[6:7], v[8:9], v[6:7]
	v_pk_mul_f32 v[4:5], v[10:11], v[4:5]
	v_pk_mul_f32 v[6:7], v[6:7], v[12:13]
	v_pk_mul_f32 v[4:5], v[4:5], v[14:15]
	v_cvt_pk_bf16_f32 v6, v6, v7
	v_cvt_pk_bf16_f32 v7, v4, v5
	global_store_dwordx2 v[20:21], v[6:7], off offset:240
	s_barrier
	s_barrier
	s_mov_b64 s[0:1], exec
	v_readlane_b32 s2, v254, 43
	v_readlane_b32 s3, v254, 44
	s_and_b64 s[2:3], s[0:1], s[2:3]
	s_mov_b64 exec, s[2:3]
	s_cbranch_execz .LBB0_2093
	s_mov_b64 s[16:17], exec
	v_mbcnt_lo_u32_b32 v2, s16, 0
	v_mbcnt_hi_u32_b32 v2, s17, v2
	v_cmp_eq_u32_e32 vcc, 0, v2
	s_and_saveexec_b64 s[2:3], vcc
	s_cbranch_execz .LBB0_2092
	s_bcnt1_i32_b64 s10, s[16:17]
	v_readlane_b32 s16, v254, 45
	v_mov_b32_e32 v4, s10
	v_readlane_b32 s17, v254, 46
	s_nop 4
	v_mov_b32_e32 v4, v255
	s_branch .LBB0_2092

; #define NEXT_UNIT() do { __syncthreads(); if (tid == 0) *UQ = (int)__hip_atomic_fetch_add(qctr, 1u, __ATOMIC_RELAXED, __HIP_MEMORY_SCOPE_AGENT); __syncthreads(); u = __builtin_amdgcn_readfirstlane(*UQ); } while (0)
; DI void p5_run(const Args& a, LAS unsigned char* lds, unsigned* qctr, const XcdBarrier& fb, unsigned* F4a, unsigned* F4b) {
;     ...
;         while (u < B4) { const int v = (u - B3) % 128; smlstm_unit(a, lds, v >> 2, v & 3); NEXT_UNIT(); }
.LBB0_2136:
	s_or_b64 exec, exec, s[16:17]
	s_barrier
	s_barrier
	s_mov_b64 s[8:9], exec
	v_readlane_b32 s16, v254, 43
	v_readlane_b32 s17, v254, 44
	s_and_b64 s[16:17], s[8:9], s[16:17]
	s_mov_b64 exec, s[16:17]
	s_cbranch_execz .LBB0_2125
	s_mov_b64 s[18:19], exec
	v_mbcnt_lo_u32_b32 v2, s18, 0
	v_mbcnt_hi_u32_b32 v2, s19, v2
	v_cmp_eq_u32_e32 vcc, 0, v2
	s_and_saveexec_b64 s[16:17], vcc
	s_cbranch_execz .LBB0_2124
	s_bcnt1_i32_b64 s0, s[18:19]
	v_readlane_b32 s18, v254, 45
	v_mov_b32_e32 v3, s0
	v_readlane_b32 s19, v254, 46
	s_nop 4
	v_mov_b32_e32 v3, v255
	s_branch .LBB0_2124

; __global__ void __launch_bounds__(NWAVES * 64, 2) fwd(Args a) {
	.amdhsa_kernel _Z3fwd4Args
		.amdhsa_group_segment_fixed_size 0
		.amdhsa_private_segment_fixed_size 0
		.amdhsa_kernarg_size 512
		.amdhsa_user_sgpr_count 2
		.amdhsa_user_sgpr_dispatch_ptr 0
		.amdhsa_user_sgpr_queue_ptr 0
		.amdhsa_user_sgpr_kernarg_segment_ptr 1
		.amdhsa_user_sgpr_dispatch_id 0
		.amdhsa_user_sgpr_kernarg_preload_length 0
		.amdhsa_user_sgpr_kernarg_preload_offset 0
		.amdhsa_user_sgpr_private_segment_size 0
		.amdhsa_uses_dynamic_stack 0
		.amdhsa_enable_private_segment 0
		.amdhsa_system_sgpr_workgroup_id_x 1
		.amdhsa_system_sgpr_workgroup_id_y 0
		.amdhsa_system_sgpr_workgroup_id_z 0
		.amdhsa_system_sgpr_workgroup_info 0
		.amdhsa_system_vgpr_workitem_id 0
		.amdhsa_next_free_vgpr 256
		.amdhsa_next_free_sgpr 102
		.amdhsa_accum_offset 256
		.amdhsa_reserve_vcc 1
		.amdhsa_float_round_mode_32 0
		.amdhsa_float_round_mode_16_64 0
		.amdhsa_float_denorm_mode_32 3
		.amdhsa_float_denorm_mode_16_64 3
		.amdhsa_dx10_clamp 1
		.amdhsa_ieee_mode 1
		.amdhsa_fp16_overflow 0
		.amdhsa_tg_split 0
		.amdhsa_exception_fp_ieee_invalid_op 0
		.amdhsa_exception_fp_denorm_src 0
		.amdhsa_exception_fp_ieee_div_zero 0
		.amdhsa_exception_fp_ieee_overflow 0
		.amdhsa_exception_fp_ieee_underflow 0
		.amdhsa_exception_fp_ieee_inexact 0
		.amdhsa_exception_int_div_zero 0
	.end_amdhsa_kernel

; __global__ void __launch_bounds__(NWAVES * 64, 2) fwd(Args a) {
amdhsa.kernels:
  - .agpr_count:     0
    .args:
      - .offset:         0
        .size:           256
        .value_kind:     by_value
      - .offset:         256
        .size:           4
        .value_kind:     hidden_block_count_x
      - .offset:         260
        .size:           4
        .value_kind:     hidden_block_count_y
      - .offset:         264
        .size:           4
        .value_kind:     hidden_block_count_z
      - .offset:         268
        .size:           2
        .value_kind:     hidden_group_size_x
      - .offset:         270
        .size:           2
        .value_kind:     hidden_group_size_y
      - .offset:         272
        .size:           2
        .value_kind:     hidden_group_size_z
      - .offset:         274
        .size:           2
        .value_kind:     hidden_remainder_x
      - .offset:         276
        .size:           2
        .value_kind:     hidden_remainder_y
      - .offset:         278
        .size:           2
        .value_kind:     hidden_remainder_z
      - .offset:         296
        .size:           8
        .value_kind:     hidden_global_offset_x
      - .offset:         304
        .size:           8
        .value_kind:     hidden_global_offset_y
      - .offset:         312
        .size:           8
        .value_kind:     hidden_global_offset_z
      - .offset:         320
        .size:           2
        .value_kind:     hidden_grid_dims
      - .offset:         376
        .size:           4
        .value_kind:     hidden_dynamic_lds_size
    .group_segment_fixed_size: 0
    .kernarg_segment_align: 8
    .kernarg_segment_size: 512
    .language:       OpenCL C
    .language_version:
      - 2
      - 0
    .max_flat_workgroup_size: 512
    .name:           _Z3fwd4Args
    .private_segment_fixed_size: 0
    .sgpr_count:     108
    .sgpr_spill_count: 232
    .symbol:         _Z3fwd4Args.kd
    .uniform_work_group_size: 1
    .uses_dynamic_stack: false
    .vgpr_count:     256
    .vgpr_spill_count: 0
    .wavefront_size: 64
